# v59 plus MLA attention QK^T blocks: K/Q fragment LDS reads renamed over 5 quads and issued early with counted lgkmcnt waits (4 steady blocks)
# speedup vs baseline: 1.0035x; 1.0035x over previous
; #define LAS __attribute__((address_space(3)))
; #define MLA_SBAR() __builtin_amdgcn_sched_barrier(0)
; __device__ __forceinline__ void finishSM(f32x16& p0, f32x16& p1, float alpha, float& l_reg, bf16x8& pa0, bf16x8& pa1, bf16x8& pa2, bf16x8& pa3) {
; #pragma unroll
;   for (int r = 0; r < 16; ++r) p1[r] = __builtin_amdgcn_exp2f(p1[r]);
;   float ps = 0;
; #pragma unroll
;   for (int r = 0; r < 16; ++r) ps += p0[r];
; #pragma unroll
;   for (int r = 0; r < 16; ++r) ps += p1[r];
;   { auto rr = __builtin_amdgcn_permlane32_swap(__float_as_uint(ps), __float_as_uint(ps), false, false);
;     ps = __uint_as_float(rr[0]) + __uint_as_float(rr[1]); }
;   l_reg = l_reg * alpha + ps;
;     ...
;   MLA_PK4(p0, 0, pa0); MLA_PK4(p0, 8, pa1); MLA_PK4(p1, 0, pa2); MLA_PK4(p1, 8, pa3);
;     ...
; }
; __device__ __forceinline__ void qkt(f32x16& p0, f32x16& p1, const unsigned Ks, const bf16x8* qr, const unsigned qrl, int r32, int hi) {
;   p0 = f32x16{}; p1 = f32x16{}; __builtin_amdgcn_s_setprio(1);
; #pragma unroll
;   for (int dg = 0; dg < 3; ++dg) {
; #pragma unroll
;     for (int d4 = 0; d4 < 4; ++d4) { const int d0 = dg * 4 + d4;
;       const bf16x8 b0 = *(const LAS bf16x8*)(size_t)(Ks + (unsigned)(r32 * KROW + hi * 16) + (unsigned)(d0 * 32));
;       const bf16x8 b1 = *(const LAS bf16x8*)(size_t)(Ks + (unsigned)(r32 * KROW + hi * 16) + (unsigned)(32 * KROW + d0 * 32));
;       const bf16x8 qv = (dg < 2) ? qr[d0 & 7] : *(const LAS bf16x8*)(size_t)(qrl + (unsigned)(d4 * 32));
;       p0 = __builtin_amdgcn_mfma_f32_32x32x16_bf16(b0, qv, p0, 0, 0, 0);
;       p1 = __builtin_amdgcn_mfma_f32_32x32x16_bf16(b1, qv, p1, 0, 0, 0); }
;     MLA_SBAR(); }
;   __builtin_amdgcn_s_setprio(0);
; }
; __device__ __forceinline__ int v_st(int k, int c) { const int kk = (k & ~0xC) | ((k & 4) << 1) | ((k & 8) >> 1); return ((kk >> 3) * 4 + (c >> 5)) * 512 + ((kk & 7) * 32 + (c & 31)) * 2; }
; __device__ __forceinline__ int v_rd_base(int lane) { return ((lane & 3) << 3) | (((lane >> 2) & 3) << 6) | (((lane >> 4) & 1) << 5) | (((lane >> 5) & 1) << 8); }
; template <int OFF> __device__ __forceinline__ s16x4 tr_read(int vb) {
;   s16x4 r; asm volatile("ds_read_b64_tr_b16 %0, %1 offset:%2" : "=&v"(r) : "v"(vb), "i"(OFF) : "memory"); return r;
; }
; template <int D0> __device__ __forceinline__ void pv_one(f32x16& od, int vb, bf16x8 pa0, bf16x8 pa1, bf16x8 pa2, bf16x8 pa3) {
.LBB0_2633:
	v_add_f32_e32 v80, 0, v158
	v_add_f32_e32 v80, v159, v80
	v_add_f32_e32 v80, v156, v80
	v_add_f32_e32 v80, v157, v80
	v_add_f32_e32 v80, v154, v80
	v_add_f32_e32 v80, v155, v80
	v_add_f32_e32 v80, v152, v80
	v_add_f32_e32 v80, v153, v80
	v_add_f32_e32 v80, v150, v80
	v_add_f32_e32 v80, v151, v80
	v_add_f32_e32 v80, v148, v80
	v_add_f32_e32 v80, v149, v80
	v_exp_f32_e32 v88, v96
	v_add_f32_e32 v80, v146, v80
	v_exp_f32_e32 v89, v97
	v_add_f32_e32 v80, v147, v80
	v_exp_f32_e32 v90, v98
	v_add_f32_e32 v80, v144, v80
	v_exp_f32_e32 v91, v99
	v_add_f32_e32 v80, v145, v80
	v_exp_f32_e32 v92, v100
	v_add_f32_e32 v80, v88, v80
	v_exp_f32_e32 v93, v101
	v_add_f32_e32 v80, v89, v80
	v_exp_f32_e32 v94, v102
	v_add_f32_e32 v80, v90, v80
	v_exp_f32_e32 v95, v103
	v_add_f32_e32 v80, v91, v80
	v_exp_f32_e32 v96, v104
	v_add_f32_e32 v80, v92, v80
	v_exp_f32_e32 v97, v105
	v_add_f32_e32 v80, v93, v80
	v_exp_f32_e32 v98, v106
	v_add_f32_e32 v80, v94, v80
	v_exp_f32_e32 v99, v107
	v_add_f32_e32 v80, v95, v80
	v_exp_f32_e32 v100, v108
	v_add_f32_e32 v80, v96, v80
	v_exp_f32_e32 v101, v109
	v_add_f32_e32 v80, v97, v80
	v_exp_f32_e32 v102, v110
	v_add_f32_e32 v80, v98, v80
	v_exp_f32_e32 v103, v111
	v_add_f32_e32 v80, v99, v80
	v_add_f32_e32 v80, v100, v80
	v_add_f32_e32 v80, v101, v80
	v_add_f32_e32 v80, v102, v80
	v_add_f32_e32 v184, v103, v80
	v_mov_b32_e32 v185, v184
	v_cvt_pk_bf16_f32 v80, v158, v159
	v_cvt_pk_bf16_f32 v81, v156, v157
	v_cvt_pk_bf16_f32 v82, v154, v155
	v_cvt_pk_bf16_f32 v83, v152, v153
	v_cvt_pk_bf16_f32 v84, v150, v151
	v_cvt_pk_bf16_f32 v85, v148, v149
	v_cvt_pk_bf16_f32 v86, v146, v147
	v_cvt_pk_bf16_f32 v87, v144, v145
	v_cvt_pk_bf16_f32 v88, v88, v89
	v_cvt_pk_bf16_f32 v89, v90, v91
	v_cvt_pk_bf16_f32 v90, v92, v93
	v_cvt_pk_bf16_f32 v91, v94, v95
	v_cvt_pk_bf16_f32 v92, v96, v97
	v_cvt_pk_bf16_f32 v93, v98, v99
	v_cvt_pk_bf16_f32 v94, v100, v101
	v_cvt_pk_bf16_f32 v95, v102, v103
	s_nop 1
	v_permlane32_swap_b32_e32 v184, v185
	v_permlane32_swap_b32_e32 v80, v82
	v_permlane32_swap_b32_e32 v81, v83
	v_permlane32_swap_b32_e32 v84, v86
	v_permlane32_swap_b32_e32 v85, v87
	v_permlane32_swap_b32_e32 v88, v90
	v_permlane32_swap_b32_e32 v89, v91
	v_permlane32_swap_b32_e32 v92, v94
	v_permlane32_swap_b32_e32 v93, v95
	s_setprio 1
	ds_read_b64_tr_b16 v[96:97], v192 offset:0
	ds_read_b64_tr_b16 v[98:99], v192 offset:0x800
	ds_read_b64_tr_b16 v[100:101], v192 offset:0x1000
	ds_read_b64_tr_b16 v[102:103], v192 offset:0x1800
	ds_read_b64_tr_b16 v[104:105], v192 offset:0x2000
	ds_read_b64_tr_b16 v[106:107], v192 offset:0x2800
	ds_read_b64_tr_b16 v[108:109], v192 offset:0x3000
	ds_read_b64_tr_b16 v[110:111], v192 offset:0x3800
	s_waitcnt lgkmcnt(0)
	s_nop 0
	v_mfma_f32_32x32x16_bf16 v[0:15], v[80:83], v[96:99], v[0:15]
	ds_read_b64_tr_b16 v[96:97], v192 offset:0x200
	ds_read_b64_tr_b16 v[98:99], v192 offset:0xa00
	v_mfma_f32_32x32x16_bf16 v[0:15], v[84:87], v[100:103], v[0:15]
	ds_read_b64_tr_b16 v[100:101], v192 offset:0x1200
	ds_read_b64_tr_b16 v[102:103], v192 offset:0x1a00
	v_mfma_f32_32x32x16_bf16 v[0:15], v[88:91], v[104:107], v[0:15]
	ds_read_b64_tr_b16 v[104:105], v192 offset:0x2200
	ds_read_b64_tr_b16 v[106:107], v192 offset:0x2a00
	ds_read_b64_tr_b16 v[144:145], v192 offset:0x3200
	ds_read_b64_tr_b16 v[146:147], v192 offset:0x3a00
	s_waitcnt lgkmcnt(0)
	v_mfma_f32_32x32x16_bf16 v[0:15], v[92:95], v[108:111], v[0:15]
	v_mfma_f32_32x32x16_bf16 v[48:63], v[80:83], v[96:99], v[48:63]
	ds_read_b64_tr_b16 v[96:97], v192 offset:0x400
	ds_read_b64_tr_b16 v[98:99], v192 offset:0xc00
	v_mfma_f32_32x32x16_bf16 v[48:63], v[84:87], v[100:103], v[48:63]
	ds_read_b64_tr_b16 v[100:101], v192 offset:0x1400
	ds_read_b64_tr_b16 v[102:103], v192 offset:0x1c00
	v_mfma_f32_32x32x16_bf16 v[48:63], v[88:91], v[104:107], v[48:63]
	ds_read_b64_tr_b16 v[104:105], v192 offset:0x2400
	ds_read_b64_tr_b16 v[106:107], v192 offset:0x2c00
	ds_read_b64_tr_b16 v[108:109], v192 offset:0x3400
	ds_read_b64_tr_b16 v[110:111], v192 offset:0x3c00
	s_waitcnt lgkmcnt(0)
	v_mfma_f32_32x32x16_bf16 v[48:63], v[92:95], v[144:147], v[48:63]
	v_mfma_f32_32x32x16_bf16 v[32:47], v[80:83], v[96:99], v[32:47]
	ds_read_b64_tr_b16 v[96:97], v192 offset:0x600
	ds_read_b64_tr_b16 v[98:99], v192 offset:0xe00
	v_mfma_f32_32x32x16_bf16 v[32:47], v[84:87], v[100:103], v[32:47]
	ds_read_b64_tr_b16 v[100:101], v192 offset:0x1600
	ds_read_b64_tr_b16 v[102:103], v192 offset:0x1e00
	v_mfma_f32_32x32x16_bf16 v[32:47], v[88:91], v[104:107], v[32:47]
	ds_read_b64_tr_b16 v[104:105], v192 offset:0x2600
	ds_read_b64_tr_b16 v[106:107], v192 offset:0x2e00
	ds_read_b64_tr_b16 v[144:145], v192 offset:0x3600
	ds_read_b64_tr_b16 v[146:147], v192 offset:0x3e00
	s_waitcnt lgkmcnt(0)
	v_mfma_f32_32x32x16_bf16 v[32:47], v[92:95], v[108:111], v[32:47]
	v_mfma_f32_32x32x16_bf16 v[16:31], v[80:83], v[96:99], v[16:31]
	v_mfma_f32_32x32x16_bf16 v[16:31], v[84:87], v[100:103], v[16:31]
	v_mfma_f32_32x32x16_bf16 v[16:31], v[88:91], v[104:107], v[16:31]
	v_mfma_f32_32x32x16_bf16 v[16:31], v[92:95], v[144:147], v[16:31]
	s_setprio 0
	v_lshl_add_u64 v[152:153], v[168:169], 0, s[60:61]
	v_add_co_u32_e32 v80, vcc, s79, v152
	v_lshl_add_u64 v[154:155], v[170:171], 0, s[60:61]
	s_nop 0
	v_addc_co_u32_e32 v81, vcc, 0, v153, vcc
	v_add_co_u32_e32 v82, vcc, s79, v154
	v_lshl_add_u64 v[156:157], v[172:173], 0, s[60:61]
	s_nop 0
	v_addc_co_u32_e32 v83, vcc, 0, v155, vcc
	global_load_dwordx4 v[144:147], v[80:81], off
	global_load_dwordx4 v[148:151], v[82:83], off
	v_add_co_u32_e32 v80, vcc, s79, v156
	v_lshl_add_u64 v[158:159], v[174:175], 0, s[60:61]
	s_nop 0
	v_addc_co_u32_e32 v81, vcc, 0, v157, vcc
	v_add_co_u32_e32 v82, vcc, s79, v158
	s_nop 1
	v_addc_co_u32_e32 v83, vcc, 0, v159, vcc
	global_load_dwordx4 v[222:225], v[80:81], off
	global_load_dwordx4 v[226:229], v[82:83], off
	global_load_dwordx4 v[230:233], v[180:181], off
	s_setprio 1
	ds_read_b128 v[80:83], v199 offset:58368
	ds_read_b128 v[234:237], v199 offset:58400
	v_add_u32_e32 v84, 0x11600, v199
	v_add_u32_e32 v161, 0x11620, v199
	s_waitcnt lgkmcnt(1)
; #define LAS __attribute__((address_space(3)))
; #define MLA_SBAR() __builtin_amdgcn_sched_barrier(0)
; __device__ __forceinline__ void partialSM(f32x16& p0, f32x16& p1, float& m_reg, float& mn, float& alpha) {
;   constexpr float C = SCALE * 1.4426950408889634f;
;   float pmax = p0[0];
; #pragma unroll
;   for (int r = 1; r < 16; ++r) pmax = fmaxf(pmax, p0[r]);
; #pragma unroll
;   for (int r = 0; r < 16; ++r) pmax = fmaxf(pmax, p1[r]);
;   { auto rr = __builtin_amdgcn_permlane32_swap(__float_as_uint(pmax), __float_as_uint(pmax), false, false);
;     pmax = fmaxf(__uint_as_float(rr[0]), __uint_as_float(rr[1])); }
;   if (__builtin_expect(__all(pmax - m_reg <= THR / SCALE), 1)) { mn = m_reg; alpha = 1.f; }
;   else { mn = fmaxf(m_reg, pmax); alpha = __builtin_amdgcn_exp2f((m_reg - mn) * C); m_reg = mn; }
; __device__ __forceinline__ void qkt(f32x16& p0, f32x16& p1, const unsigned Ks, const bf16x8* qr, const unsigned qrl, int r32, int hi) {
;   p0 = f32x16{}; p1 = f32x16{}; __builtin_amdgcn_s_setprio(1);
; #pragma unroll
;   for (int dg = 0; dg < 3; ++dg) {
; #pragma unroll
;     for (int d4 = 0; d4 < 4; ++d4) { const int d0 = dg * 4 + d4;
;       const bf16x8 b0 = *(const LAS bf16x8*)(size_t)(Ks + (unsigned)(r32 * KROW + hi * 16) + (unsigned)(d0 * 32));
;       const bf16x8 b1 = *(const LAS bf16x8*)(size_t)(Ks + (unsigned)(r32 * KROW + hi * 16) + (unsigned)(32 * KROW + d0 * 32));
;       const bf16x8 qv = (dg < 2) ? qr[d0 & 7] : *(const LAS bf16x8*)(size_t)(qrl + (unsigned)(d4 * 32));
;       p0 = __builtin_amdgcn_mfma_f32_32x32x16_bf16(b0, qv, p0, 0, 0, 0);
;       p1 = __builtin_amdgcn_mfma_f32_32x32x16_bf16(b1, qv, p1, 0, 0, 0); }
;     MLA_SBAR(); }
;   __builtin_amdgcn_s_setprio(0);
; }
	v_mfma_f32_32x32x16_bf16 v[96:111], v[80:83], v[140:143], 0
	ds_read_b128 v[80:83], v84
	ds_read_b128 v[238:241], v199 offset:58464
	ds_read_b128 v[242:245], v161
	ds_read_b128 v[246:249], v199 offset:58432
	s_waitcnt lgkmcnt(4)
	v_mfma_f32_32x32x16_bf16 v[96:111], v[234:237], v[136:139], v[96:111]
	v_add_u32_e32 v161, 0x11640, v199
	ds_read_b128 v[250:253], v161
	s_waitcnt lgkmcnt(4)
	v_mfma_f32_32x32x16_bf16 v[80:95], v[80:83], v[140:143], 0
	s_waitcnt lgkmcnt(2)
	v_mfma_f32_32x32x16_bf16 v[80:95], v[242:245], v[136:139], v[80:95]
	s_waitcnt lgkmcnt(1)
	v_mfma_f32_32x32x16_bf16 v[96:111], v[246:249], v[132:135], v[96:111]
	v_add_u32_e32 v161, 0x11660, v199
	ds_read_b128 v[234:237], v161
	s_waitcnt lgkmcnt(1)
	v_mfma_f32_32x32x16_bf16 v[80:95], v[250:253], v[132:135], v[80:95]
	v_mfma_f32_32x32x16_bf16 v[96:111], v[238:241], v[128:131], v[96:111]
	ds_read_b128 v[238:241], v199 offset:58496
	ds_read_b128 v[242:245], v199 offset:58528
	s_waitcnt lgkmcnt(2)
	v_mfma_f32_32x32x16_bf16 v[80:95], v[234:237], v[128:131], v[80:95]
	v_add_u32_e32 v161, 0x11680, v199
	ds_read_b128 v[246:249], v161
	ds_read_b128 v[250:253], v199 offset:58592
	s_waitcnt lgkmcnt(3)
	v_mfma_f32_32x32x16_bf16 v[96:111], v[238:241], v[124:127], v[96:111]
	v_add_u32_e32 v161, 0x116a0, v199
	ds_read_b128 v[234:237], v161
	ds_read_b128 v[238:241], v199 offset:58560
	s_waitcnt lgkmcnt(4)
	v_mfma_f32_32x32x16_bf16 v[96:111], v[242:245], v[120:123], v[96:111]
	s_waitcnt lgkmcnt(3)
	v_mfma_f32_32x32x16_bf16 v[80:95], v[246:249], v[124:127], v[80:95]
	v_add_u32_e32 v161, 0x116c0, v199
	ds_read_b128 v[242:245], v161
	s_waitcnt lgkmcnt(2)
	v_mfma_f32_32x32x16_bf16 v[80:95], v[234:237], v[120:123], v[80:95]
	s_waitcnt lgkmcnt(1)
	v_mfma_f32_32x32x16_bf16 v[96:111], v[238:241], v[116:119], v[96:111]
	v_add_u32_e32 v161, 0x116e0, v199
	ds_read_b128 v[246:249], v161
	s_waitcnt lgkmcnt(1)
	v_mfma_f32_32x32x16_bf16 v[80:95], v[242:245], v[116:119], v[80:95]
	v_mfma_f32_32x32x16_bf16 v[96:111], v[250:253], v[112:115], v[96:111]
	ds_read_b128 v[250:253], v199 offset:58624
	ds_read_b128 v[234:237], v193
	ds_read_b128 v[238:241], v199 offset:58656
	s_waitcnt lgkmcnt(3)
	v_mfma_f32_32x32x16_bf16 v[80:95], v[246:249], v[112:115], v[80:95]
	v_add_u32_e32 v161, 0x11700, v199
	ds_read_b128 v[242:245], v161
	s_waitcnt lgkmcnt(2)
	v_mfma_f32_32x32x16_bf16 v[96:111], v[250:253], v[234:237], v[96:111]
	v_add_u32_e32 v161, 0x11720, v199
	ds_read_b128 v[246:249], v161
	ds_read_b128 v[250:253], v195
	s_waitcnt lgkmcnt(2)
	v_mfma_f32_32x32x16_bf16 v[80:95], v[242:245], v[234:237], v[80:95]
	ds_read_b128 v[234:237], v199 offset:58688
	v_add_u32_e32 v161, 0x11740, v199
	s_waitcnt lgkmcnt(1)
	v_mfma_f32_32x32x16_bf16 v[96:111], v[238:241], v[250:253], v[96:111]
	ds_read_b128 v[238:241], v196
	ds_read_b128 v[242:245], v199 offset:58720
	v_mfma_f32_32x32x16_bf16 v[80:95], v[246:249], v[250:253], v[80:95]
	ds_read_b128 v[246:249], v161
	s_waitcnt lgkmcnt(2)
	v_mfma_f32_32x32x16_bf16 v[96:111], v[234:237], v[238:241], v[96:111]
	v_add_u32_e32 v161, 0x11760, v199
	ds_read_b128 v[250:253], v161
	ds_read_b128 v[234:237], v194
	s_waitcnt lgkmcnt(2)
	v_mfma_f32_32x32x16_bf16 v[80:95], v[246:249], v[238:241], v[80:95]
	s_waitcnt lgkmcnt(0)
	v_mfma_f32_32x32x16_bf16 v[96:111], v[242:245], v[234:237], v[96:111]
	v_mfma_f32_32x32x16_bf16 v[80:95], v[250:253], v[234:237], v[80:95]
	s_setprio 0
	s_nop 9
	v_max_f32_e32 v161, v97, v97
	v_max_f32_e32 v162, v96, v96
	v_max_f32_e32 v161, v162, v161
	v_max3_f32 v161, v161, v98, v99
	v_max3_f32 v161, v161, v100, v101
	v_max3_f32 v161, v161, v102, v103
	v_max3_f32 v161, v161, v104, v105
	v_max3_f32 v161, v161, v106, v107
	v_max3_f32 v161, v161, v108, v109
	v_max3_f32 v161, v161, v110, v111
	v_max3_f32 v161, v161, v80, v81
	v_max3_f32 v161, v161, v82, v83
	v_max3_f32 v161, v161, v84, v85
	v_max3_f32 v161, v161, v86, v87
	v_max3_f32 v161, v161, v88, v89
	v_max3_f32 v161, v161, v90, v91
	v_max3_f32 v161, v161, v92, v93
	v_max3_f32 v161, v161, v94, v95
	v_mov_b32_e32 v162, v161
	s_nop 1
	v_permlane32_swap_b32_e32 v161, v162
	v_max_f32_e32 v162, v162, v162
	v_max_f32_e32 v161, v161, v161
	v_max_f32_e32 v161, v161, v162
	v_sub_f32_e32 v162, v161, v160
	v_cmp_ge_f32_e32 vcc, s75, v162
	v_max_f32_e32 v162, v160, v160
	v_max_f32_e32 v161, v162, v161
	v_sub_f32_e32 v162, v160, v161
	v_mul_f32_e32 v162, 0x3dd53b94, v162
	v_exp_f32_e32 v162, v162
	s_cmp_eq_u64 vcc, exec
	s_cselect_b64 s[4:5], -1, 0
	s_barrier
	s_waitcnt vmcnt(0)
	v_cndmask_b32_e64 v186, v162, 1.0, s[4:5]
	v_add_u32_e32 v187, 0, v176
	s_waitcnt vmcnt(4)
	ds_write_b128 v200, v[144:147]
	s_waitcnt vmcnt(3)
	ds_write_b128 v201, v[148:151]
	s_waitcnt vmcnt(2)
	ds_write_b128 v187, v[222:225] offset:32768
	s_waitcnt vmcnt(1)
	ds_write_b128 v187, v[226:229] offset:45568
	v_add_u32_e32 v222, 0, v202
	v_cmp_gt_f32_e32 vcc, 1.0, v186
	s_waitcnt vmcnt(0)
	ds_write_b128 v222, v[230:233] offset:32768
	s_cbranch_vccz .LBB0_2637
	s_and_saveexec_b64 s[62:63], s[2:3]
	ds_write_b32 v177, v186 offset:128
	s_or_b64 exec, exec, s[62:63]
	s_waitcnt lgkmcnt(0)
	v_add_u32_e32 v182, v167, v164
	ds_read2_b32 v[144:145], v182 offset0:48 offset1:49
	ds_read2_b32 v[146:147], v182 offset0:50 offset1:51
	ds_read2_b32 v[148:149], v182 offset0:56 offset1:57
	ds_read2_b32 v[150:151], v182 offset0:58 offset1:59
	ds_read2_b32 v[162:163], v182 offset0:32 offset1:33
	ds_read2_b32 v[224:225], v182 offset0:34 offset1:35
	ds_read2_b32 v[226:227], v182 offset0:40 offset1:41
	ds_read2_b32 v[228:229], v182 offset0:42 offset1:43
	s_waitcnt lgkmcnt(4)
	v_pk_mul_f32 v[14:15], v[14:15], v[150:151]
	v_pk_mul_f32 v[12:13], v[12:13], v[148:149]
	v_pk_mul_f32 v[10:11], v[10:11], v[146:147]
	v_pk_mul_f32 v[8:9], v[8:9], v[144:145]
	s_waitcnt lgkmcnt(0)
	v_pk_mul_f32 v[6:7], v[6:7], v[228:229]
	v_pk_mul_f32 v[4:5], v[4:5], v[226:227]
	v_pk_mul_f32 v[2:3], v[2:3], v[224:225]
	v_pk_mul_f32 v[0:1], v[0:1], v[162:163]
	v_pk_mul_f32 v[62:63], v[62:63], v[150:151]
	v_pk_mul_f32 v[60:61], v[60:61], v[148:149]
	v_pk_mul_f32 v[58:59], v[58:59], v[146:147]
	v_pk_mul_f32 v[56:57], v[56:57], v[144:145]
	v_pk_mul_f32 v[54:55], v[54:55], v[228:229]
	v_pk_mul_f32 v[52:53], v[52:53], v[226:227]
	v_pk_mul_f32 v[50:51], v[50:51], v[224:225]
	v_pk_mul_f32 v[48:49], v[48:49], v[162:163]
	v_pk_mul_f32 v[46:47], v[46:47], v[150:151]
	v_pk_mul_f32 v[44:45], v[44:45], v[148:149]
	v_pk_mul_f32 v[42:43], v[42:43], v[146:147]
	v_pk_mul_f32 v[40:41], v[40:41], v[144:145]
	v_pk_mul_f32 v[38:39], v[38:39], v[228:229]
	v_pk_mul_f32 v[36:37], v[36:37], v[226:227]
	v_pk_mul_f32 v[34:35], v[34:35], v[224:225]
	v_pk_mul_f32 v[32:33], v[32:33], v[162:163]
	v_pk_mul_f32 v[30:31], v[30:31], v[150:151]
	v_pk_mul_f32 v[28:29], v[28:29], v[148:149]
	v_pk_mul_f32 v[26:27], v[26:27], v[146:147]
	v_pk_mul_f32 v[24:25], v[24:25], v[144:145]
	v_pk_mul_f32 v[22:23], v[22:23], v[228:229]
	v_pk_mul_f32 v[20:21], v[20:21], v[226:227]
	v_pk_mul_f32 v[18:19], v[18:19], v[224:225]
	v_pk_mul_f32 v[16:17], v[16:17], v[162:163]
; #define MLA_SBAR() __builtin_amdgcn_sched_barrier(0)
; __device__ __forceinline__ void partialSM(f32x16& p0, f32x16& p1, float& m_reg, float& mn, float& alpha) {
;     ...
;   float mnC = -mn * C;
; #pragma unroll
;   for (int r = 0; r < 16; ++r) p0[r] = fmaf(p0[r], C, mnC);
; #pragma unroll
;   for (int r = 0; r < 16; ++r) p1[r] = fmaf(p1[r], C, mnC);
; #pragma unroll
;   for (int r = 0; r < 16; ++r) p0[r] = __builtin_amdgcn_exp2f(p0[r]);
; }
; __device__ __forceinline__ void finishSM(f32x16& p0, f32x16& p1, float alpha, float& l_reg, bf16x8& pa0, bf16x8& pa1, bf16x8& pa2, bf16x8& pa3) {
; #pragma unroll
;   for (int r = 0; r < 16; ++r) p1[r] = __builtin_amdgcn_exp2f(p1[r]);
;   float ps = 0;
; #pragma unroll
;   for (int r = 0; r < 16; ++r) ps += p0[r];
; #pragma unroll
;   for (int r = 0; r < 16; ++r) ps += p1[r];
;   { auto rr = __builtin_amdgcn_permlane32_swap(__float_as_uint(ps), __float_as_uint(ps), false, false);
;     ps = __uint_as_float(rr[0]) + __uint_as_float(rr[1]); }
;   l_reg = l_reg * alpha + ps;
;     ...
;   MLA_PK4(p0, 0, pa0); MLA_PK4(p0, 8, pa1); MLA_PK4(p1, 0, pa2); MLA_PK4(p1, 8, pa3);
; template <int D0> __device__ __forceinline__ void pv_one(f32x16& od, int vb, bf16x8 pa0, bf16x8 pa1, bf16x8 pa2, bf16x8 pa3) {
;   const s16x4 l0 = tr_read<v_rd_off(D0, 0, 0)>(vb), h0 = tr_read<v_rd_off(D0, 0, 1)>(vb), l1 = tr_read<v_rd_off(D0, 1, 0)>(vb), h1 = tr_read<v_rd_off(D0, 1, 1)>(vb);
;   const s16x4 l2 = tr_read<v_rd_off(D0, 2, 0)>(vb), h2 = tr_read<v_rd_off(D0, 2, 1)>(vb), l3 = tr_read<v_rd_off(D0, 3, 0)>(vb), h3 = tr_read<v_rd_off(D0, 3, 1)>(vb);
;   asm volatile("s_waitcnt lgkmcnt(0)" ::: "memory"); MLA_SBAR();
;     ...
;   od = __builtin_amdgcn_mfma_f32_32x32x16_bf16(pa0, MLA_PK(l0, h0), od, 0, 0, 0);
;   od = __builtin_amdgcn_mfma_f32_32x32x16_bf16(pa1, MLA_PK(l1, h1), od, 0, 0, 0);
;   od = __builtin_amdgcn_mfma_f32_32x32x16_bf16(pa2, MLA_PK(l2, h2), od, 0, 0, 0);
;   od = __builtin_amdgcn_mfma_f32_32x32x16_bf16(pa3, MLA_PK(l3, h3), od, 0, 0, 0);
;     ...
; }
.LBB0_2637:
	v_cndmask_b32_e64 v223, v161, v160, s[4:5]
	v_mul_f32_e32 v144, 0xbdd53b94, v223
	v_fmamk_f32 v96, v96, 0x3dd53b94, v144
	v_fmamk_f32 v97, v97, 0x3dd53b94, v144
	v_fmamk_f32 v145, v98, 0x3dd53b94, v144
	v_fmamk_f32 v146, v99, 0x3dd53b94, v144
	v_fmamk_f32 v147, v100, 0x3dd53b94, v144
	v_fmamk_f32 v148, v101, 0x3dd53b94, v144
	v_fmamk_f32 v149, v102, 0x3dd53b94, v144
	v_fmamk_f32 v150, v103, 0x3dd53b94, v144
	v_fmamk_f32 v151, v104, 0x3dd53b94, v144
	v_fmamk_f32 v160, v105, 0x3dd53b94, v144
	v_fmamk_f32 v161, v106, 0x3dd53b94, v144
	v_fmamk_f32 v162, v107, 0x3dd53b94, v144
	v_fmamk_f32 v163, v108, 0x3dd53b94, v144
	v_fmamk_f32 v182, v109, 0x3dd53b94, v144
	v_fmamk_f32 v224, v110, 0x3dd53b94, v144
	v_fmamk_f32 v225, v111, 0x3dd53b94, v144
	v_fmamk_f32 v99, v80, 0x3dd53b94, v144
	v_fmamk_f32 v100, v81, 0x3dd53b94, v144
	v_fmamk_f32 v101, v82, 0x3dd53b94, v144
	v_fmamk_f32 v102, v83, 0x3dd53b94, v144
	v_fmamk_f32 v103, v84, 0x3dd53b94, v144
	v_fmamk_f32 v104, v85, 0x3dd53b94, v144
	v_fmamk_f32 v105, v86, 0x3dd53b94, v144
	v_fmamk_f32 v106, v87, 0x3dd53b94, v144
	v_fmamk_f32 v107, v88, 0x3dd53b94, v144
	v_fmamk_f32 v108, v89, 0x3dd53b94, v144
	v_fmamk_f32 v109, v90, 0x3dd53b94, v144
	v_fmamk_f32 v110, v91, 0x3dd53b94, v144
	v_fmamk_f32 v111, v92, 0x3dd53b94, v144
	v_exp_f32_e32 v96, v96
	v_exp_f32_e32 v98, v97
	v_exp_f32_e32 v91, v145
	v_exp_f32_e32 v97, v146
	v_exp_f32_e32 v89, v147
	v_exp_f32_e32 v92, v148
	v_exp_f32_e32 v88, v149
	v_exp_f32_e32 v90, v150
	v_exp_f32_e32 v85, v151
	v_exp_f32_e32 v87, v160
	v_exp_f32_e32 v83, v161
	v_exp_f32_e32 v86, v162
	v_exp_f32_e32 v81, v163
	v_exp_f32_e32 v84, v182
	v_exp_f32_e32 v80, v224
	v_exp_f32_e32 v82, v225
	v_fmamk_f32 v93, v93, 0x3dd53b94, v144
	v_fmamk_f32 v94, v94, 0x3dd53b94, v144
	v_fmac_f32_e32 v144, 0x3dd53b94, v95
	s_waitcnt lgkmcnt(0)
	s_barrier
	v_exp_f32_e32 v145, v94
	v_add_f32_e32 v94, 0, v96
	v_add_f32_e32 v94, v98, v94
	v_add_f32_e32 v94, v91, v94
	v_add_f32_e32 v94, v97, v94
	v_add_f32_e32 v94, v89, v94
	v_add_f32_e32 v94, v92, v94
	v_add_f32_e32 v94, v88, v94
	v_add_f32_e32 v94, v90, v94
	v_add_f32_e32 v94, v85, v94
	v_add_f32_e32 v94, v87, v94
	v_add_f32_e32 v94, v83, v94
	v_add_f32_e32 v94, v86, v94
	v_exp_f32_e32 v99, v99
	v_add_f32_e32 v94, v81, v94
	v_exp_f32_e32 v100, v100
	v_add_f32_e32 v94, v84, v94
	v_exp_f32_e32 v101, v101
	v_add_f32_e32 v94, v80, v94
	v_exp_f32_e32 v102, v102
	v_add_f32_e32 v94, v82, v94
	v_exp_f32_e32 v103, v103
	v_add_f32_e32 v94, v99, v94
	v_exp_f32_e32 v104, v104
	v_add_f32_e32 v94, v100, v94
	v_exp_f32_e32 v105, v105
	v_add_f32_e32 v94, v101, v94
	v_exp_f32_e32 v106, v106
	v_add_f32_e32 v94, v102, v94
	v_exp_f32_e32 v107, v107
	v_add_f32_e32 v94, v103, v94
	v_exp_f32_e32 v108, v108
	v_add_f32_e32 v94, v104, v94
	v_exp_f32_e32 v109, v109
	v_add_f32_e32 v94, v105, v94
	v_exp_f32_e32 v110, v110
	v_add_f32_e32 v94, v106, v94
	v_exp_f32_e32 v111, v111
	v_add_f32_e32 v94, v107, v94
	v_exp_f32_e32 v93, v93
	v_add_f32_e32 v94, v108, v94
	v_add_f32_e32 v94, v109, v94
	v_exp_f32_e32 v144, v144
	v_add_f32_e32 v94, v110, v94
	v_add_f32_e32 v94, v111, v94
	v_add_f32_e32 v94, v93, v94
	v_add_f32_e32 v94, v145, v94
	v_add_f32_e32 v224, v144, v94
	v_mov_b32_e32 v225, v224
	v_cvt_pk_bf16_f32 v94, v96, v98
	v_cvt_pk_bf16_f32 v95, v91, v97
	v_cvt_pk_bf16_f32 v96, v89, v92
	v_cvt_pk_bf16_f32 v97, v88, v90
	v_cvt_pk_bf16_f32 v88, v85, v87
	v_cvt_pk_bf16_f32 v89, v83, v86
	v_cvt_pk_bf16_f32 v90, v81, v84
	v_cvt_pk_bf16_f32 v91, v80, v82
	v_cvt_pk_bf16_f32 v80, v99, v100
	v_cvt_pk_bf16_f32 v81, v101, v102
	v_cvt_pk_bf16_f32 v82, v103, v104
	v_cvt_pk_bf16_f32 v83, v105, v106
	v_cvt_pk_bf16_f32 v84, v107, v108
	v_cvt_pk_bf16_f32 v85, v109, v110
	v_cvt_pk_bf16_f32 v86, v111, v93
	v_cvt_pk_bf16_f32 v87, v145, v144
	s_nop 1
	v_permlane32_swap_b32_e32 v224, v225
	v_permlane32_swap_b32_e32 v94, v96
	v_permlane32_swap_b32_e32 v95, v97
	v_permlane32_swap_b32_e32 v88, v90
	v_permlane32_swap_b32_e32 v89, v91
	v_permlane32_swap_b32_e32 v80, v82
	v_permlane32_swap_b32_e32 v81, v83
	v_permlane32_swap_b32_e32 v84, v86
	v_permlane32_swap_b32_e32 v85, v87
	s_setprio 1
	ds_read_b64_tr_b16 v[98:99], v197 offset:0
	ds_read_b64_tr_b16 v[100:101], v197 offset:0x800
	ds_read_b64_tr_b16 v[102:103], v197 offset:0x1000
	ds_read_b64_tr_b16 v[104:105], v197 offset:0x1800
	ds_read_b64_tr_b16 v[106:107], v197 offset:0x2000
	ds_read_b64_tr_b16 v[108:109], v197 offset:0x2800
	ds_read_b64_tr_b16 v[144:145], v197 offset:0x3000
	ds_read_b64_tr_b16 v[146:147], v197 offset:0x3800
	s_waitcnt lgkmcnt(0)
	s_nop 0
	v_mfma_f32_32x32x16_bf16 v[0:15], v[94:97], v[98:101], v[0:15]
	ds_read_b64_tr_b16 v[98:99], v197 offset:0x200
	ds_read_b64_tr_b16 v[100:101], v197 offset:0xa00
	v_mfma_f32_32x32x16_bf16 v[0:15], v[88:91], v[102:105], v[0:15]
	ds_read_b64_tr_b16 v[102:103], v197 offset:0x1200
	ds_read_b64_tr_b16 v[104:105], v197 offset:0x1a00
	v_mfma_f32_32x32x16_bf16 v[0:15], v[80:83], v[106:109], v[0:15]
	ds_read_b64_tr_b16 v[106:107], v197 offset:0x2200
	ds_read_b64_tr_b16 v[108:109], v197 offset:0x2a00
	ds_read_b64_tr_b16 v[148:149], v197 offset:0x3200
	ds_read_b64_tr_b16 v[150:151], v197 offset:0x3a00
	s_waitcnt lgkmcnt(0)
	v_mfma_f32_32x32x16_bf16 v[0:15], v[84:87], v[144:147], v[0:15]
	v_mfma_f32_32x32x16_bf16 v[48:63], v[94:97], v[98:101], v[48:63]
	ds_read_b64_tr_b16 v[98:99], v197 offset:0x400
	ds_read_b64_tr_b16 v[100:101], v197 offset:0xc00
	v_mfma_f32_32x32x16_bf16 v[48:63], v[88:91], v[102:105], v[48:63]
	ds_read_b64_tr_b16 v[102:103], v197 offset:0x1400
	ds_read_b64_tr_b16 v[104:105], v197 offset:0x1c00
	v_mfma_f32_32x32x16_bf16 v[48:63], v[80:83], v[106:109], v[48:63]
	ds_read_b64_tr_b16 v[106:107], v197 offset:0x2400
	ds_read_b64_tr_b16 v[108:109], v197 offset:0x2c00
	ds_read_b64_tr_b16 v[144:145], v197 offset:0x3400
	ds_read_b64_tr_b16 v[146:147], v197 offset:0x3c00
	s_waitcnt lgkmcnt(0)
; #define LAS __attribute__((address_space(3)))
; #define MLA_SBAR() __builtin_amdgcn_sched_barrier(0)
; #define MLA_SLOAD(k0) do { const GAS bf16* vt_ = Vh + (size_t)(k0) * ldkv; const GAS bf16* kt_ = Kn + (size_t)(k0) * ldkv; const GAS bf16* rt_ = Kr + (size_t)(k0) * 64; \
;     vs0 = *(const GAS bf16x8*)(vt_ + goff0); vs1 = *(const GAS bf16x8*)(vt_ + goff1); ks0 = *(const GAS bf16x8*)(kt_ + goff0); ks1 = *(const GAS bf16x8*)(kt_ + goff1); kr0 = *(const GAS bf16x8*)(rt_ + goffr); } while (0)
; __device__ __forceinline__ void qkt(f32x16& p0, f32x16& p1, const unsigned Ks, const bf16x8* qr, const unsigned qrl, int r32, int hi) {
;   p0 = f32x16{}; p1 = f32x16{}; __builtin_amdgcn_s_setprio(1);
; #pragma unroll
;   for (int dg = 0; dg < 3; ++dg) {
; #pragma unroll
;     for (int d4 = 0; d4 < 4; ++d4) { const int d0 = dg * 4 + d4;
;       const bf16x8 b0 = *(const LAS bf16x8*)(size_t)(Ks + (unsigned)(r32 * KROW + hi * 16) + (unsigned)(d0 * 32));
;       const bf16x8 b1 = *(const LAS bf16x8*)(size_t)(Ks + (unsigned)(r32 * KROW + hi * 16) + (unsigned)(32 * KROW + d0 * 32));
;       const bf16x8 qv = (dg < 2) ? qr[d0 & 7] : *(const LAS bf16x8*)(size_t)(qrl + (unsigned)(d4 * 32));
;       p0 = __builtin_amdgcn_mfma_f32_32x32x16_bf16(b0, qv, p0, 0, 0, 0);
;       p1 = __builtin_amdgcn_mfma_f32_32x32x16_bf16(b1, qv, p1, 0, 0, 0); }
;     MLA_SBAR(); }
;   __builtin_amdgcn_s_setprio(0);
; }
; __device__ __forceinline__ void attn_body(const GAS bf16* __restrict__ Qb, const int ldq, const GAS bf16* __restrict__ Kn, const GAS bf16* __restrict__ Vh, const int ldkv, const GAS bf16* __restrict__ Kr, ...
;     ...
;     MLA_SLOAD((j + 2) * KVBLK); MLA_SBAR();
;     qkt(pA0, pA1, K_lds, qr, qrl, r32, hi); partialSM(pA0, pA1, m_reg, mnA, alA);
	v_mfma_f32_32x32x16_bf16 v[48:63], v[84:87], v[148:151], v[48:63]
	v_mfma_f32_32x32x16_bf16 v[32:47], v[94:97], v[98:101], v[32:47]
	ds_read_b64_tr_b16 v[98:99], v197 offset:0x600
	ds_read_b64_tr_b16 v[100:101], v197 offset:0xe00
	v_mfma_f32_32x32x16_bf16 v[32:47], v[88:91], v[102:105], v[32:47]
	ds_read_b64_tr_b16 v[102:103], v197 offset:0x1600
	ds_read_b64_tr_b16 v[104:105], v197 offset:0x1e00
	v_mfma_f32_32x32x16_bf16 v[32:47], v[80:83], v[106:109], v[32:47]
	ds_read_b64_tr_b16 v[106:107], v197 offset:0x2600
	ds_read_b64_tr_b16 v[108:109], v197 offset:0x2e00
	ds_read_b64_tr_b16 v[148:149], v197 offset:0x3600
	ds_read_b64_tr_b16 v[150:151], v197 offset:0x3e00
	s_waitcnt lgkmcnt(0)
	v_mfma_f32_32x32x16_bf16 v[32:47], v[84:87], v[144:147], v[32:47]
	v_mfma_f32_32x32x16_bf16 v[16:31], v[94:97], v[98:101], v[16:31]
	v_mfma_f32_32x32x16_bf16 v[16:31], v[88:91], v[102:105], v[16:31]
	v_mfma_f32_32x32x16_bf16 v[16:31], v[80:83], v[106:109], v[16:31]
	v_mfma_f32_32x32x16_bf16 v[16:31], v[84:87], v[148:151], v[16:31]
	s_setprio 0
	v_add_co_u32_e32 v80, vcc, s80, v152
	s_nop 1
	v_addc_co_u32_e32 v81, vcc, 0, v153, vcc
	v_add_co_u32_e32 v82, vcc, s80, v154
	s_nop 1
	v_addc_co_u32_e32 v83, vcc, 0, v155, vcc
	global_load_dwordx4 v[144:147], v[80:81], off
	global_load_dwordx4 v[148:151], v[82:83], off
	v_add_co_u32_e32 v80, vcc, s80, v156
	s_nop 1
	v_addc_co_u32_e32 v81, vcc, 0, v157, vcc
	v_add_co_u32_e32 v82, vcc, s80, v158
	s_nop 1
	v_addc_co_u32_e32 v83, vcc, 0, v159, vcc
	global_load_dwordx4 v[152:155], v[80:81], off
	global_load_dwordx4 v[156:159], v[82:83], off
	v_add_co_u32_e32 v80, vcc, s76, v180
	s_nop 1
	v_addc_co_u32_e32 v81, vcc, 0, v181, vcc
	global_load_dwordx4 v[160:163], v[80:81], off
	s_setprio 1
	ds_read_b128 v[80:83], v199 offset:32768
	ds_read_b128 v[226:229], v199 offset:32800
	s_waitcnt lgkmcnt(1)
	v_mfma_f32_32x32x16_bf16 v[96:111], v[80:83], v[140:143], 0
	ds_read_b128 v[80:83], v199 offset:45568
	ds_read_b128 v[230:233], v199 offset:45600
	ds_read_b128 v[234:237], v199 offset:32832
	ds_read_b128 v[238:241], v199 offset:32864
	ds_read_b128 v[246:249], v199 offset:45632
	ds_read_b128 v[250:253], v199 offset:45664
	s_waitcnt lgkmcnt(5)
	v_mfma_f32_32x32x16_bf16 v[80:95], v[80:83], v[140:143], 0
	v_mfma_f32_32x32x16_bf16 v[96:111], v[226:229], v[136:139], v[96:111]
	ds_read_b128 v[226:229], v199 offset:32896
	s_waitcnt lgkmcnt(5)
	v_mfma_f32_32x32x16_bf16 v[80:95], v[230:233], v[136:139], v[80:95]
	ds_read_b128 v[230:233], v199 offset:32928
	s_waitcnt lgkmcnt(5)
	v_mfma_f32_32x32x16_bf16 v[96:111], v[234:237], v[132:135], v[96:111]
	ds_read_b128 v[234:237], v199 offset:45696
	s_waitcnt lgkmcnt(4)
	v_mfma_f32_32x32x16_bf16 v[80:95], v[246:249], v[132:135], v[80:95]
	v_mfma_f32_32x32x16_bf16 v[96:111], v[238:241], v[128:131], v[96:111]
	ds_read_b128 v[238:241], v199 offset:45728
	ds_read_b128 v[246:249], v199 offset:32960
	s_waitcnt lgkmcnt(5)
	v_mfma_f32_32x32x16_bf16 v[80:95], v[250:253], v[128:131], v[80:95]
	ds_read_b128 v[250:253], v199 offset:32992
	s_waitcnt lgkmcnt(5)
	v_mfma_f32_32x32x16_bf16 v[96:111], v[226:229], v[124:127], v[96:111]
	ds_read_b128 v[226:229], v199 offset:45760
	s_waitcnt lgkmcnt(4)
	v_mfma_f32_32x32x16_bf16 v[80:95], v[234:237], v[124:127], v[80:95]
	v_mfma_f32_32x32x16_bf16 v[96:111], v[230:233], v[120:123], v[96:111]
	ds_read_b128 v[230:233], v199 offset:45792
	ds_read_b128 v[234:237], v199 offset:33024
	s_waitcnt lgkmcnt(5)
	v_mfma_f32_32x32x16_bf16 v[80:95], v[238:241], v[120:123], v[80:95]
	ds_read_b128 v[238:241], v193
	s_waitcnt lgkmcnt(5)
	v_mfma_f32_32x32x16_bf16 v[96:111], v[246:249], v[116:119], v[96:111]
	ds_read_b128 v[246:249], v199 offset:33056
	s_waitcnt lgkmcnt(4)
	v_mfma_f32_32x32x16_bf16 v[80:95], v[226:229], v[116:119], v[80:95]
	v_mfma_f32_32x32x16_bf16 v[96:111], v[250:253], v[112:115], v[96:111]
	ds_read_b128 v[250:253], v199 offset:45824
	ds_read_b128 v[226:229], v199 offset:45856
	s_waitcnt lgkmcnt(5)
	v_mfma_f32_32x32x16_bf16 v[80:95], v[230:233], v[112:115], v[80:95]
	ds_read_b128 v[230:233], v195
	s_waitcnt lgkmcnt(4)
	v_mfma_f32_32x32x16_bf16 v[96:111], v[234:237], v[238:241], v[96:111]
	ds_read_b128 v[234:237], v199 offset:33088
	s_waitcnt lgkmcnt(3)
	v_mfma_f32_32x32x16_bf16 v[80:95], v[250:253], v[238:241], v[80:95]
	ds_read_b128 v[238:241], v196
	s_waitcnt lgkmcnt(2)
	v_mfma_f32_32x32x16_bf16 v[96:111], v[246:249], v[230:233], v[96:111]
	ds_read_b128 v[246:249], v199 offset:33120
	ds_read_b128 v[250:253], v199 offset:45888
	v_mfma_f32_32x32x16_bf16 v[80:95], v[226:229], v[230:233], v[80:95]
	ds_read_b128 v[226:229], v199 offset:45920
	ds_read_b128 v[230:233], v194
	s_waitcnt lgkmcnt(4)
	v_mfma_f32_32x32x16_bf16 v[96:111], v[234:237], v[238:241], v[96:111]
	s_waitcnt lgkmcnt(2)
	v_mfma_f32_32x32x16_bf16 v[80:95], v[250:253], v[238:241], v[80:95]
	s_waitcnt lgkmcnt(0)
	v_mfma_f32_32x32x16_bf16 v[96:111], v[246:249], v[230:233], v[96:111]
	v_mfma_f32_32x32x16_bf16 v[80:95], v[226:229], v[230:233], v[80:95]
	s_setprio 0
	s_nop 9
	v_max_f32_e32 v182, v97, v97
	v_max_f32_e32 v226, v96, v96
	v_max_f32_e32 v182, v226, v182
	v_max3_f32 v182, v182, v98, v99
	v_max3_f32 v182, v182, v100, v101
	v_max3_f32 v182, v182, v102, v103
	v_max3_f32 v182, v182, v104, v105
	v_max3_f32 v182, v182, v106, v107
	v_max3_f32 v182, v182, v108, v109
	v_max3_f32 v182, v182, v110, v111
	v_max3_f32 v182, v182, v80, v81
	v_max3_f32 v182, v182, v82, v83
	v_max3_f32 v182, v182, v84, v85
	v_max3_f32 v182, v182, v86, v87
	v_max3_f32 v182, v182, v88, v89
	v_max3_f32 v182, v182, v90, v91
	v_max3_f32 v182, v182, v92, v93
	v_max3_f32 v182, v182, v94, v95
	v_mov_b32_e32 v226, v182
	s_nop 1
	v_permlane32_swap_b32_e32 v182, v226
	v_max_f32_e32 v226, v226, v226
	v_max_f32_e32 v182, v182, v182
	v_max_f32_e32 v182, v182, v226
	v_sub_f32_e32 v226, v182, v223
	v_cmp_ge_f32_e32 vcc, s75, v226
	v_max_f32_e32 v226, v223, v223
	v_max_f32_e32 v226, v226, v182
	v_sub_f32_e32 v182, v223, v226
	v_mul_f32_e32 v182, 0x3dd53b94, v182
	v_exp_f32_e32 v182, v182
	s_cmp_eq_u64 vcc, exec
	s_cselect_b64 s[4:5], -1, 0
	s_barrier
; #define MLA_SWAIT() asm volatile("s_waitcnt vmcnt(0)" ::: "memory")
; #define MLA_RESC(a) do { if (__any((a) < 1.f)) { if (hi == 0) al_l[r32] = (a); asm volatile("s_waitcnt lgkmcnt(0)" ::: "memory"); \
;     _Pragma("unroll") for (int d = 0; d < 4; ++d) _Pragma("unroll") for (int r = 0; r < 16; ++r) o[d][r] *= al_l[crow(r, hi)]; } } while (0)
; __device__ __forceinline__ void attn_body(const GAS bf16* __restrict__ Qb, const int ldq, const GAS bf16* __restrict__ Kn, const GAS bf16* __restrict__ Vh, const int ldkv, const GAS bf16* __restrict__ Kr, ...
;     ...
;     __syncthreads(); MLA_SWAIT(); MLA_SWRITE(1);
;     MLA_RESC(alA); __syncthreads();
	s_waitcnt vmcnt(0)
	v_cndmask_b32_e64 v182, v182, 1.0, s[4:5]
	v_cmp_gt_f32_e32 vcc, 1.0, v182
	s_waitcnt vmcnt(4)
	ds_write_b128 v200, v[144:147] offset:16384
	s_waitcnt vmcnt(3)
	ds_write_b128 v201, v[148:151] offset:16384
	s_waitcnt vmcnt(2)
	ds_write_b128 v187, v[152:155] offset:58368
	s_waitcnt vmcnt(1)
	ds_write_b128 v204, v[156:159] offset:12800
	s_waitcnt vmcnt(0)
	ds_write_b128 v222, v[160:163] offset:58368
	s_cbranch_vccz .LBB0_2641
	s_and_saveexec_b64 s[62:63], s[2:3]
	ds_write_b32 v177, v182 offset:128
	s_or_b64 exec, exec, s[62:63]
	s_waitcnt lgkmcnt(0)
	v_add_u32_e32 v158, v167, v164
	ds_read2_b32 v[144:145], v158 offset0:48 offset1:49
	ds_read2_b32 v[146:147], v158 offset0:50 offset1:51
	ds_read2_b32 v[148:149], v158 offset0:56 offset1:57
	ds_read2_b32 v[150:151], v158 offset0:58 offset1:59
	ds_read2_b32 v[152:153], v158 offset0:32 offset1:33
	ds_read2_b32 v[154:155], v158 offset0:34 offset1:35
	ds_read2_b32 v[156:157], v158 offset0:40 offset1:41
	ds_read2_b32 v[158:159], v158 offset0:42 offset1:43
	s_waitcnt lgkmcnt(4)
	v_pk_mul_f32 v[14:15], v[14:15], v[150:151]
	v_pk_mul_f32 v[12:13], v[12:13], v[148:149]
	v_pk_mul_f32 v[10:11], v[10:11], v[146:147]
	v_pk_mul_f32 v[8:9], v[8:9], v[144:145]
	s_waitcnt lgkmcnt(0)
	v_pk_mul_f32 v[6:7], v[6:7], v[158:159]
	v_pk_mul_f32 v[4:5], v[4:5], v[156:157]
	v_pk_mul_f32 v[2:3], v[2:3], v[154:155]
	v_pk_mul_f32 v[0:1], v[0:1], v[152:153]
	v_pk_mul_f32 v[62:63], v[62:63], v[150:151]
	v_pk_mul_f32 v[60:61], v[60:61], v[148:149]
	v_pk_mul_f32 v[58:59], v[58:59], v[146:147]
	v_pk_mul_f32 v[56:57], v[56:57], v[144:145]
	v_pk_mul_f32 v[54:55], v[54:55], v[158:159]
	v_pk_mul_f32 v[52:53], v[52:53], v[156:157]
	v_pk_mul_f32 v[50:51], v[50:51], v[154:155]
	v_pk_mul_f32 v[48:49], v[48:49], v[152:153]
	v_pk_mul_f32 v[46:47], v[46:47], v[150:151]
	v_pk_mul_f32 v[44:45], v[44:45], v[148:149]
	v_pk_mul_f32 v[42:43], v[42:43], v[146:147]
	v_pk_mul_f32 v[40:41], v[40:41], v[144:145]
	v_pk_mul_f32 v[38:39], v[38:39], v[158:159]
	v_pk_mul_f32 v[36:37], v[36:37], v[156:157]
	v_pk_mul_f32 v[34:35], v[34:35], v[154:155]
	v_pk_mul_f32 v[32:33], v[32:33], v[152:153]
	v_pk_mul_f32 v[30:31], v[30:31], v[150:151]
	v_pk_mul_f32 v[28:29], v[28:29], v[148:149]
	v_pk_mul_f32 v[26:27], v[26:27], v[146:147]
	v_pk_mul_f32 v[24:25], v[24:25], v[144:145]
	v_pk_mul_f32 v[22:23], v[22:23], v[158:159]
	v_pk_mul_f32 v[20:21], v[20:21], v[156:157]
	v_pk_mul_f32 v[18:19], v[18:19], v[154:155]
	v_pk_mul_f32 v[16:17], v[16:17], v[152:153]

; #define LAS __attribute__((address_space(3)))
; #define MLA_SBAR() __builtin_amdgcn_sched_barrier(0)
; #define MLA_SLOAD(k0) do { const GAS bf16* vt_ = Vh + (size_t)(k0) * ldkv; const GAS bf16* kt_ = Kn + (size_t)(k0) * ldkv; const GAS bf16* rt_ = Kr + (size_t)(k0) * 64; \
;     vs0 = *(const GAS bf16x8*)(vt_ + goff0); vs1 = *(const GAS bf16x8*)(vt_ + goff1); ks0 = *(const GAS bf16x8*)(kt_ + goff0); ks1 = *(const GAS bf16x8*)(kt_ + goff1); kr0 = *(const GAS bf16x8*)(rt_ + goffr); } while (0)
; __device__ __forceinline__ void qkt(f32x16& p0, f32x16& p1, const unsigned Ks, const bf16x8* qr, const unsigned qrl, int r32, int hi) {
;   p0 = f32x16{}; p1 = f32x16{}; __builtin_amdgcn_s_setprio(1);
; #pragma unroll
;   for (int dg = 0; dg < 3; ++dg) {
; #pragma unroll
;     for (int d4 = 0; d4 < 4; ++d4) { const int d0 = dg * 4 + d4;
;       const bf16x8 b0 = *(const LAS bf16x8*)(size_t)(Ks + (unsigned)(r32 * KROW + hi * 16) + (unsigned)(d0 * 32));
;       const bf16x8 b1 = *(const LAS bf16x8*)(size_t)(Ks + (unsigned)(r32 * KROW + hi * 16) + (unsigned)(32 * KROW + d0 * 32));
;       const bf16x8 qv = (dg < 2) ? qr[d0 & 7] : *(const LAS bf16x8*)(size_t)(qrl + (unsigned)(d4 * 32));
;       p0 = __builtin_amdgcn_mfma_f32_32x32x16_bf16(b0, qv, p0, 0, 0, 0);
;       p1 = __builtin_amdgcn_mfma_f32_32x32x16_bf16(b1, qv, p1, 0, 0, 0); }
;     MLA_SBAR(); }
;   __builtin_amdgcn_s_setprio(0);
; }
; __device__ __forceinline__ void attn_body(const GAS bf16* __restrict__ Qb, const int ldq, const GAS bf16* __restrict__ Kn, const GAS bf16* __restrict__ Vh, const int ldkv, const GAS bf16* __restrict__ Kr, ...
;     ...
;   for (int j = 1; j + 1 < NT; j += 2) {
;     MLA_SBAR(); qkt(pB0, pB1, K_lds + SHM_K, qr, qrl, r32, hi); MLA_SBAR();
;     MLA_SLOAD((j + 1) * KVBLK); MLA_SBAR();
;     partialSM(pB0, pB1, m_reg, mnB, alB); finishSM(pA0, pA1, alA, l_reg, pa0, pa1, pa2, pa3); MLA_SBAR();
.LBB0_2646:
	s_setprio 1
	ds_read_b128 v[80:83], v199 offset:58368
	ds_read_b128 v[144:147], v199 offset:58400
	v_add_u32_e32 v84, 0x11600, v199
	v_add_u32_e32 v148, 0x11620, v199
	v_add_u32_e32 v152, 0x11640, v199
	s_waitcnt lgkmcnt(1)
	v_mfma_f32_32x32x16_bf16 v[96:111], v[80:83], v[140:143], 0
	ds_read_b128 v[80:83], v84
	s_waitcnt lgkmcnt(1)
	v_mfma_f32_32x32x16_bf16 v[96:111], v[144:147], v[136:139], v[96:111]
	ds_read_b128 v[144:147], v148
	ds_read_b128 v[148:151], v199 offset:58464
	s_waitcnt lgkmcnt(2)
	v_mfma_f32_32x32x16_bf16 v[80:95], v[80:83], v[140:143], 0
	s_waitcnt lgkmcnt(1)
	v_mfma_f32_32x32x16_bf16 v[80:95], v[144:147], v[136:139], v[80:95]
	ds_read_b128 v[144:147], v199 offset:58432
	s_waitcnt lgkmcnt(0)
	v_mfma_f32_32x32x16_bf16 v[96:111], v[144:147], v[132:135], v[96:111]
	ds_read_b128 v[144:147], v152
	s_waitcnt lgkmcnt(0)
	v_mfma_f32_32x32x16_bf16 v[80:95], v[144:147], v[132:135], v[80:95]
	v_add_u32_e32 v144, 0x11660, v199
	ds_read_b128 v[144:147], v144
	v_mfma_f32_32x32x16_bf16 v[96:111], v[148:151], v[128:131], v[96:111]
	s_waitcnt lgkmcnt(0)
	v_mfma_f32_32x32x16_bf16 v[80:95], v[144:147], v[128:131], v[80:95]
	ds_read_b128 v[144:147], v199 offset:58496
	ds_read_b128 v[148:151], v199 offset:58528
	v_add_u32_e32 v152, 0x11680, v199
	s_waitcnt lgkmcnt(1)
	v_mfma_f32_32x32x16_bf16 v[96:111], v[144:147], v[124:127], v[96:111]
	ds_read_b128 v[144:147], v152
	v_add_u32_e32 v152, 0x116c0, v199
	s_waitcnt lgkmcnt(1)
	v_mfma_f32_32x32x16_bf16 v[96:111], v[148:151], v[120:123], v[96:111]
	ds_read_b128 v[148:151], v199 offset:58592
	s_waitcnt lgkmcnt(1)
	v_mfma_f32_32x32x16_bf16 v[80:95], v[144:147], v[124:127], v[80:95]
	v_add_u32_e32 v144, 0x116a0, v199
	ds_read_b128 v[144:147], v144
	s_waitcnt lgkmcnt(0)
	v_mfma_f32_32x32x16_bf16 v[80:95], v[144:147], v[120:123], v[80:95]
	ds_read_b128 v[144:147], v199 offset:58560
	s_waitcnt lgkmcnt(0)
	v_mfma_f32_32x32x16_bf16 v[96:111], v[144:147], v[116:119], v[96:111]
	ds_read_b128 v[144:147], v152
	s_waitcnt lgkmcnt(0)
	v_mfma_f32_32x32x16_bf16 v[80:95], v[144:147], v[116:119], v[80:95]
	v_add_u32_e32 v144, 0x116e0, v199
	ds_read_b128 v[144:147], v144
	v_mfma_f32_32x32x16_bf16 v[96:111], v[148:151], v[112:115], v[96:111]
	s_waitcnt lgkmcnt(0)
	v_mfma_f32_32x32x16_bf16 v[80:95], v[144:147], v[112:115], v[80:95]
	ds_read_b128 v[144:147], v199 offset:58624
	ds_read_b128 v[148:151], v193
	ds_read_b128 v[152:155], v199 offset:58656
	v_add_u32_e32 v156, 0x11700, v199
	s_waitcnt lgkmcnt(1)
	v_mfma_f32_32x32x16_bf16 v[96:111], v[144:147], v[148:151], v[96:111]
	ds_read_b128 v[144:147], v156
	v_add_u32_e32 v156, 0x11740, v199
	s_waitcnt lgkmcnt(0)
	v_mfma_f32_32x32x16_bf16 v[80:95], v[144:147], v[148:151], v[80:95]
	v_add_u32_e32 v148, 0x11720, v199
	ds_read_b128 v[148:151], v148
	ds_read_b128 v[144:147], v195
	s_waitcnt lgkmcnt(0)
	v_mfma_f32_32x32x16_bf16 v[96:111], v[152:155], v[144:147], v[96:111]
	v_mfma_f32_32x32x16_bf16 v[80:95], v[148:151], v[144:147], v[80:95]
	ds_read_b128 v[144:147], v199 offset:58688
	ds_read_b128 v[148:151], v196
	ds_read_b128 v[152:155], v199 offset:58720
	s_waitcnt lgkmcnt(1)
	v_mfma_f32_32x32x16_bf16 v[96:111], v[144:147], v[148:151], v[96:111]
	ds_read_b128 v[144:147], v156
	s_waitcnt lgkmcnt(0)
	v_mfma_f32_32x32x16_bf16 v[80:95], v[144:147], v[148:151], v[80:95]
	v_add_u32_e32 v148, 0x11760, v199
	ds_read_b128 v[148:151], v148
	ds_read_b128 v[144:147], v194
	s_waitcnt lgkmcnt(0)
	v_mfma_f32_32x32x16_bf16 v[96:111], v[152:155], v[144:147], v[96:111]
	v_mfma_f32_32x32x16_bf16 v[80:95], v[148:151], v[144:147], v[80:95]
	s_setprio 0
	v_lshl_add_u64 v[180:181], v[168:169], 0, s[60:61]
	v_add_co_u32_e32 v144, vcc, s79, v180
	v_lshl_add_u64 v[182:183], v[170:171], 0, s[60:61]
	s_nop 0
	v_addc_co_u32_e32 v145, vcc, 0, v181, vcc
	v_add_co_u32_e32 v148, vcc, s79, v182
	v_lshl_add_u64 v[184:185], v[172:173], 0, s[60:61]
	s_nop 0
	v_addc_co_u32_e32 v149, vcc, 0, v183, vcc
	v_add_co_u32_e32 v152, vcc, s79, v184
	v_lshl_add_u64 v[186:187], v[174:175], 0, s[60:61]
	s_nop 0
	v_addc_co_u32_e32 v153, vcc, 0, v185, vcc
	v_add_co_u32_e32 v156, vcc, s79, v186
	global_load_dwordx4 v[144:147], v[144:145], off
	s_nop 0
	global_load_dwordx4 v[148:151], v[148:149], off
	v_addc_co_u32_e32 v157, vcc, 0, v187, vcc
	global_load_dwordx4 v[152:155], v[152:153], off
	s_nop 0
	global_load_dwordx4 v[160:163], v[156:157], off
	s_nop 0
	global_load_dwordx4 v[156:159], v[178:179], off
	v_exp_f32_e32 v226, v64
	v_add_f32_e32 v64, 0, v206
	v_add_f32_e32 v64, v208, v64
	v_add_f32_e32 v64, v209, v64
	v_add_f32_e32 v64, v212, v64
	v_add_f32_e32 v64, v213, v64
	v_max_f32_e32 v222, v97, v97
	v_max_f32_e32 v223, v96, v96
	v_add_f32_e32 v64, v216, v64
	v_max_f32_e32 v222, v223, v222
	v_add_f32_e32 v64, v217, v64
	v_max3_f32 v222, v222, v98, v99
	v_add_f32_e32 v64, v220, v64
	v_max3_f32 v222, v222, v100, v101
	v_add_f32_e32 v64, v207, v64
	v_max3_f32 v222, v222, v102, v103
	v_add_f32_e32 v64, v210, v64
	v_max3_f32 v222, v222, v104, v105
	v_add_f32_e32 v64, v211, v64
	v_max3_f32 v222, v222, v106, v107
	v_add_f32_e32 v64, v214, v64
	v_max3_f32 v222, v222, v108, v109
	v_add_f32_e32 v64, v215, v64
	v_max3_f32 v222, v222, v110, v111
	v_exp_f32_e32 v227, v65
	v_add_f32_e32 v64, v218, v64
	v_max3_f32 v222, v222, v80, v81
	v_exp_f32_e32 v228, v66
	v_add_f32_e32 v64, v219, v64
	v_max3_f32 v222, v222, v82, v83
	v_exp_f32_e32 v229, v67
	v_add_f32_e32 v64, v221, v64
	v_max3_f32 v222, v222, v84, v85
	v_exp_f32_e32 v230, v68
	v_add_f32_e32 v64, v226, v64
	v_max3_f32 v222, v222, v86, v87
	v_exp_f32_e32 v231, v69
	v_add_f32_e32 v64, v227, v64
	v_max3_f32 v222, v222, v88, v89
	v_exp_f32_e32 v232, v70
; #define MLA_SWAIT() asm volatile("s_waitcnt vmcnt(0)" ::: "memory")
; __device__ __forceinline__ void partialSM(f32x16& p0, f32x16& p1, float& m_reg, float& mn, float& alpha) {
;     ...
;   { auto rr = __builtin_amdgcn_permlane32_swap(__float_as_uint(pmax), __float_as_uint(pmax), false, false);
;     pmax = fmaxf(__uint_as_float(rr[0]), __uint_as_float(rr[1])); }
;   if (__builtin_expect(__all(pmax - m_reg <= THR / SCALE), 1)) { mn = m_reg; alpha = 1.f; }
;   else { mn = fmaxf(m_reg, pmax); alpha = __builtin_amdgcn_exp2f((m_reg - mn) * C); m_reg = mn; }
;   float mnC = -mn * C;
; #pragma unroll
;   for (int r = 0; r < 16; ++r) p0[r] = fmaf(p0[r], C, mnC);
; #pragma unroll
;   for (int r = 0; r < 16; ++r) p1[r] = fmaf(p1[r], C, mnC);
; #pragma unroll
;   for (int r = 0; r < 16; ++r) p0[r] = __builtin_amdgcn_exp2f(p0[r]);
; }
; __device__ __forceinline__ void finishSM(f32x16& p0, f32x16& p1, float alpha, float& l_reg, bf16x8& pa0, bf16x8& pa1, bf16x8& pa2, bf16x8& pa3) {
; #pragma unroll
;   for (int r = 0; r < 16; ++r) p1[r] = __builtin_amdgcn_exp2f(p1[r]);
;   float ps = 0;
; #pragma unroll
;   for (int r = 0; r < 16; ++r) ps += p0[r];
; #pragma unroll
;   for (int r = 0; r < 16; ++r) ps += p1[r];
;   { auto rr = __builtin_amdgcn_permlane32_swap(__float_as_uint(ps), __float_as_uint(ps), false, false);
;     ps = __uint_as_float(rr[0]) + __uint_as_float(rr[1]); }
;   l_reg = l_reg * alpha + ps;
;     ...
;   MLA_PK4(p0, 0, pa0); MLA_PK4(p0, 8, pa1); MLA_PK4(p1, 0, pa2); MLA_PK4(p1, 8, pa3);
; __device__ __forceinline__ void attn_body(const GAS bf16* __restrict__ Qb, const int ldq, const GAS bf16* __restrict__ Kn, const GAS bf16* __restrict__ Vh, const int ldkv, const GAS bf16* __restrict__ Kr, ...
;     ...
;     pv_d0(o, vb0, pa0, pa1, pa2, pa3);
;     __syncthreads(); MLA_SWAIT(); MLA_SWRITE(0);
	v_add_f32_e32 v64, v228, v64
	v_max3_f32 v222, v222, v90, v91
	v_exp_f32_e32 v233, v71
	v_add_f32_e32 v64, v229, v64
	v_max3_f32 v222, v222, v92, v93
	v_exp_f32_e32 v234, v72
	v_add_f32_e32 v64, v230, v64
	v_max3_f32 v222, v222, v94, v95
	v_exp_f32_e32 v235, v73
	v_add_f32_e32 v64, v231, v64
	v_mov_b32_e32 v223, v222
	v_exp_f32_e32 v236, v74
	v_add_f32_e32 v64, v232, v64
	v_permlane32_swap_b32_e32 v222, v223
	v_exp_f32_e32 v237, v75
	v_add_f32_e32 v64, v233, v64
	v_max_f32_e32 v223, v223, v223
	v_max_f32_e32 v222, v222, v222
	v_exp_f32_e32 v238, v76
	v_add_f32_e32 v64, v234, v64
	v_max_f32_e32 v222, v222, v223
	v_max_f32_e32 v224, v205, v205
	v_exp_f32_e32 v239, v77
	v_add_f32_e32 v64, v235, v64
	v_max_f32_e32 v225, v224, v222
	v_exp_f32_e32 v240, v78
	v_add_f32_e32 v64, v236, v64
	v_sub_f32_e32 v223, v222, v205
	v_sub_f32_e32 v222, v205, v225
	v_exp_f32_e32 v79, v79
	v_add_f32_e32 v64, v237, v64
	v_mul_f32_e32 v222, 0x3dd53b94, v222
	v_add_f32_e32 v64, v238, v64
	v_exp_f32_e32 v222, v222
	v_add_f32_e32 v64, v239, v64
	v_cmp_ge_f32_e32 vcc, s75, v223
	v_add_f32_e32 v64, v240, v64
	s_cmp_eq_u64 vcc, exec
	v_add_f32_e32 v223, v79, v64
	s_cselect_b64 s[4:5], -1, 0
	v_mov_b32_e32 v224, v223
	v_cndmask_b32_e64 v222, v222, 1.0, s[4:5]
	s_nop 0
	v_permlane32_swap_b32_e32 v223, v224
	v_cvt_pk_bf16_f32 v64, v206, v208
	v_cvt_pk_bf16_f32 v65, v209, v212
	v_cvt_pk_bf16_f32 v66, v213, v216
	v_cvt_pk_bf16_f32 v67, v217, v220
	v_cvt_pk_bf16_f32 v68, v207, v210
	v_cvt_pk_bf16_f32 v69, v211, v214
	v_cvt_pk_bf16_f32 v70, v215, v218
	v_cvt_pk_bf16_f32 v71, v219, v221
	v_cvt_pk_bf16_f32 v72, v226, v227
	v_cvt_pk_bf16_f32 v73, v228, v229
	v_cvt_pk_bf16_f32 v74, v230, v231
	v_cvt_pk_bf16_f32 v75, v232, v233
	v_cvt_pk_bf16_f32 v76, v234, v235
	v_cvt_pk_bf16_f32 v77, v236, v237
	v_cvt_pk_bf16_f32 v78, v238, v239
	v_cvt_pk_bf16_f32 v79, v240, v79
	s_nop 0
	v_permlane32_swap_b32_e32 v64, v66
	v_permlane32_swap_b32_e32 v65, v67
	v_permlane32_swap_b32_e32 v68, v70
	v_permlane32_swap_b32_e32 v69, v71
	v_permlane32_swap_b32_e32 v72, v74
	v_permlane32_swap_b32_e32 v73, v75
	v_permlane32_swap_b32_e32 v76, v78
	v_permlane32_swap_b32_e32 v77, v79
	s_setprio 1
	ds_read_b64_tr_b16 v[206:207], v192 offset:0
	ds_read_b64_tr_b16 v[208:209], v192 offset:0x800
	ds_read_b64_tr_b16 v[210:211], v192 offset:0x1000
	ds_read_b64_tr_b16 v[212:213], v192 offset:0x1800
	ds_read_b64_tr_b16 v[214:215], v192 offset:0x2000
	ds_read_b64_tr_b16 v[216:217], v192 offset:0x2800
	ds_read_b64_tr_b16 v[218:219], v192 offset:0x3000
	ds_read_b64_tr_b16 v[220:221], v192 offset:0x3800
	s_waitcnt lgkmcnt(0)
	s_nop 0
	v_mfma_f32_32x32x16_bf16 v[0:15], v[64:67], v[206:209], v[0:15]
	ds_read_b64_tr_b16 v[206:207], v192 offset:0x200
	ds_read_b64_tr_b16 v[208:209], v192 offset:0xa00
	v_mfma_f32_32x32x16_bf16 v[0:15], v[68:71], v[210:213], v[0:15]
	ds_read_b64_tr_b16 v[210:211], v192 offset:0x1200
	ds_read_b64_tr_b16 v[212:213], v192 offset:0x1a00
	v_mfma_f32_32x32x16_bf16 v[0:15], v[72:75], v[214:217], v[0:15]
	ds_read_b64_tr_b16 v[214:215], v192 offset:0x2200
	ds_read_b64_tr_b16 v[216:217], v192 offset:0x2a00
	v_mfma_f32_32x32x16_bf16 v[0:15], v[76:79], v[218:221], v[0:15]
	ds_read_b64_tr_b16 v[218:219], v192 offset:0x3200
	ds_read_b64_tr_b16 v[220:221], v192 offset:0x3a00
	s_waitcnt lgkmcnt(0)
	v_mfma_f32_32x32x16_bf16 v[48:63], v[64:67], v[206:209], v[48:63]
	ds_read_b64_tr_b16 v[206:207], v192 offset:0x400
	ds_read_b64_tr_b16 v[208:209], v192 offset:0xc00
	v_mfma_f32_32x32x16_bf16 v[48:63], v[68:71], v[210:213], v[48:63]
	ds_read_b64_tr_b16 v[210:211], v192 offset:0x1400
	ds_read_b64_tr_b16 v[212:213], v192 offset:0x1c00
	v_mfma_f32_32x32x16_bf16 v[48:63], v[72:75], v[214:217], v[48:63]
	ds_read_b64_tr_b16 v[214:215], v192 offset:0x2400
	ds_read_b64_tr_b16 v[216:217], v192 offset:0x2c00
	v_mfma_f32_32x32x16_bf16 v[48:63], v[76:79], v[218:221], v[48:63]
	ds_read_b64_tr_b16 v[218:219], v192 offset:0x3400
	ds_read_b64_tr_b16 v[220:221], v192 offset:0x3c00
	s_waitcnt lgkmcnt(0)
	v_mfma_f32_32x32x16_bf16 v[32:47], v[64:67], v[206:209], v[32:47]
	ds_read_b64_tr_b16 v[206:207], v192 offset:0x600
	ds_read_b64_tr_b16 v[208:209], v192 offset:0xe00
	v_mfma_f32_32x32x16_bf16 v[32:47], v[68:71], v[210:213], v[32:47]
	ds_read_b64_tr_b16 v[210:211], v192 offset:0x1600
	ds_read_b64_tr_b16 v[212:213], v192 offset:0x1e00
	v_mfma_f32_32x32x16_bf16 v[32:47], v[72:75], v[214:217], v[32:47]
	ds_read_b64_tr_b16 v[214:215], v192 offset:0x2600
	ds_read_b64_tr_b16 v[216:217], v192 offset:0x2e00
	v_mfma_f32_32x32x16_bf16 v[32:47], v[76:79], v[218:221], v[32:47]
	ds_read_b64_tr_b16 v[218:219], v192 offset:0x3600
	ds_read_b64_tr_b16 v[220:221], v192 offset:0x3e00
	s_waitcnt lgkmcnt(0)
	v_mfma_f32_32x32x16_bf16 v[16:31], v[64:67], v[206:209], v[16:31]
	v_mfma_f32_32x32x16_bf16 v[16:31], v[68:71], v[210:213], v[16:31]
	v_mfma_f32_32x32x16_bf16 v[16:31], v[72:75], v[214:217], v[16:31]
	v_mfma_f32_32x32x16_bf16 v[16:31], v[76:79], v[218:221], v[16:31]
	s_setprio 0
	s_barrier
	s_waitcnt vmcnt(0)
	s_waitcnt vmcnt(4)
	ds_write_b128 v200, v[144:147]
	s_waitcnt vmcnt(3)
	ds_write_b128 v201, v[148:151]
	v_add_u32_e32 v148, 0, v176
	v_add_u32_e32 v149, 0, v202
	v_cmp_gt_f32_e32 vcc, 1.0, v222
	s_waitcnt vmcnt(2)
	ds_write_b128 v148, v[152:155] offset:32768
	s_waitcnt vmcnt(1)
	ds_write_b128 v148, v[160:163] offset:45568
	s_waitcnt vmcnt(0)
	ds_write_b128 v149, v[156:159] offset:32768
	s_cbranch_vccz .LBB0_2650
; #define LAS __attribute__((address_space(3)))
; #define MLA_SBAR() __builtin_amdgcn_sched_barrier(0)
; __device__ __forceinline__ void partialSM(f32x16& p0, f32x16& p1, float& m_reg, float& mn, float& alpha) {
;     ...
;   float mnC = -mn * C;
; #pragma unroll
;   for (int r = 0; r < 16; ++r) p0[r] = fmaf(p0[r], C, mnC);
; #pragma unroll
;   for (int r = 0; r < 16; ++r) p1[r] = fmaf(p1[r], C, mnC);
; #pragma unroll
;   for (int r = 0; r < 16; ++r) p0[r] = __builtin_amdgcn_exp2f(p0[r]);
; }
; __device__ __forceinline__ void finishSM(f32x16& p0, f32x16& p1, float alpha, float& l_reg, bf16x8& pa0, bf16x8& pa1, bf16x8& pa2, bf16x8& pa3) {
; #pragma unroll
;   for (int r = 0; r < 16; ++r) p1[r] = __builtin_amdgcn_exp2f(p1[r]);
;   float ps = 0;
; #pragma unroll
;   for (int r = 0; r < 16; ++r) ps += p0[r];
; #pragma unroll
;   for (int r = 0; r < 16; ++r) ps += p1[r];
;   { auto rr = __builtin_amdgcn_permlane32_swap(__float_as_uint(ps), __float_as_uint(ps), false, false);
;     ps = __uint_as_float(rr[0]) + __uint_as_float(rr[1]); }
;   l_reg = l_reg * alpha + ps;
;     ...
;   MLA_PK4(p0, 0, pa0); MLA_PK4(p0, 8, pa1); MLA_PK4(p1, 0, pa2); MLA_PK4(p1, 8, pa3);
;     ...
; }
; __device__ __forceinline__ void qkt(f32x16& p0, f32x16& p1, const unsigned Ks, const bf16x8* qr, const unsigned qrl, int r32, int hi) {
;   p0 = f32x16{}; p1 = f32x16{}; __builtin_amdgcn_s_setprio(1);
; #pragma unroll
;   for (int dg = 0; dg < 3; ++dg) {
; #pragma unroll
;     for (int d4 = 0; d4 < 4; ++d4) { const int d0 = dg * 4 + d4;
;       const bf16x8 b0 = *(const LAS bf16x8*)(size_t)(Ks + (unsigned)(r32 * KROW + hi * 16) + (unsigned)(d0 * 32));
;       const bf16x8 b1 = *(const LAS bf16x8*)(size_t)(Ks + (unsigned)(r32 * KROW + hi * 16) + (unsigned)(32 * KROW + d0 * 32));
;       const bf16x8 qv = (dg < 2) ? qr[d0 & 7] : *(const LAS bf16x8*)(size_t)(qrl + (unsigned)(d4 * 32));
;       p0 = __builtin_amdgcn_mfma_f32_32x32x16_bf16(b0, qv, p0, 0, 0, 0);
;       p1 = __builtin_amdgcn_mfma_f32_32x32x16_bf16(b1, qv, p1, 0, 0, 0); }
;     MLA_SBAR(); }
;   __builtin_amdgcn_s_setprio(0);
; }
	s_and_saveexec_b64 s[62:63], s[2:3]
	ds_write_b32 v177, v222 offset:128
	s_or_b64 exec, exec, s[62:63]
	s_waitcnt lgkmcnt(0)
	v_add_u32_e32 v78, v167, v164
	ds_read2_b32 v[64:65], v78 offset0:48 offset1:49
	ds_read2_b32 v[66:67], v78 offset0:50 offset1:51
	ds_read2_b32 v[68:69], v78 offset0:56 offset1:57
	ds_read2_b32 v[70:71], v78 offset0:58 offset1:59
	ds_read2_b32 v[72:73], v78 offset0:32 offset1:33
	ds_read2_b32 v[74:75], v78 offset0:34 offset1:35
	ds_read2_b32 v[76:77], v78 offset0:40 offset1:41
	ds_read2_b32 v[78:79], v78 offset0:42 offset1:43
	s_waitcnt lgkmcnt(4)
	v_pk_mul_f32 v[14:15], v[14:15], v[70:71]
	v_pk_mul_f32 v[12:13], v[12:13], v[68:69]
	v_pk_mul_f32 v[10:11], v[10:11], v[66:67]
	v_pk_mul_f32 v[8:9], v[8:9], v[64:65]
	s_waitcnt lgkmcnt(0)
	v_pk_mul_f32 v[6:7], v[6:7], v[78:79]
	v_pk_mul_f32 v[4:5], v[4:5], v[76:77]
	v_pk_mul_f32 v[2:3], v[2:3], v[74:75]
	v_pk_mul_f32 v[0:1], v[0:1], v[72:73]
	v_pk_mul_f32 v[62:63], v[62:63], v[70:71]
	v_pk_mul_f32 v[60:61], v[60:61], v[68:69]
	v_pk_mul_f32 v[58:59], v[58:59], v[66:67]
	v_pk_mul_f32 v[56:57], v[56:57], v[64:65]
	v_pk_mul_f32 v[54:55], v[54:55], v[78:79]
	v_pk_mul_f32 v[52:53], v[52:53], v[76:77]
	v_pk_mul_f32 v[50:51], v[50:51], v[74:75]
	v_pk_mul_f32 v[48:49], v[48:49], v[72:73]
	v_pk_mul_f32 v[46:47], v[46:47], v[70:71]
	v_pk_mul_f32 v[44:45], v[44:45], v[68:69]
	v_pk_mul_f32 v[42:43], v[42:43], v[66:67]
	v_pk_mul_f32 v[40:41], v[40:41], v[64:65]
	v_pk_mul_f32 v[38:39], v[38:39], v[78:79]
	v_pk_mul_f32 v[36:37], v[36:37], v[76:77]
	v_pk_mul_f32 v[34:35], v[34:35], v[74:75]
	v_pk_mul_f32 v[32:33], v[32:33], v[72:73]
	v_pk_mul_f32 v[30:31], v[30:31], v[70:71]
	v_pk_mul_f32 v[28:29], v[28:29], v[68:69]
	v_pk_mul_f32 v[26:27], v[26:27], v[66:67]
	v_pk_mul_f32 v[24:25], v[24:25], v[64:65]
	v_pk_mul_f32 v[22:23], v[22:23], v[78:79]
	v_pk_mul_f32 v[20:21], v[20:21], v[76:77]
	v_pk_mul_f32 v[18:19], v[18:19], v[74:75]
	v_pk_mul_f32 v[16:17], v[16:17], v[72:73]
.LBB0_2650:
	v_cndmask_b32_e64 v150, v225, v205, s[4:5]
	v_mul_f32_e32 v151, 0xbdd53b94, v150
	v_fmamk_f32 v64, v96, 0x3dd53b94, v151
	v_fmamk_f32 v65, v97, 0x3dd53b94, v151
	v_fmamk_f32 v66, v98, 0x3dd53b94, v151
	v_fmamk_f32 v67, v99, 0x3dd53b94, v151
	v_fmamk_f32 v68, v100, 0x3dd53b94, v151
	v_fmamk_f32 v69, v101, 0x3dd53b94, v151
	v_fmamk_f32 v70, v102, 0x3dd53b94, v151
	v_fmamk_f32 v71, v103, 0x3dd53b94, v151
	v_fmamk_f32 v72, v104, 0x3dd53b94, v151
	v_fmamk_f32 v73, v105, 0x3dd53b94, v151
	v_fmamk_f32 v74, v106, 0x3dd53b94, v151
	v_fmamk_f32 v75, v107, 0x3dd53b94, v151
	v_fmamk_f32 v76, v108, 0x3dd53b94, v151
	v_fmamk_f32 v77, v109, 0x3dd53b94, v151
	v_fmamk_f32 v78, v110, 0x3dd53b94, v151
	v_fmamk_f32 v79, v111, 0x3dd53b94, v151
	v_fmamk_f32 v152, v80, 0x3dd53b94, v151
	v_fmamk_f32 v211, v81, 0x3dd53b94, v151
	v_fmamk_f32 v212, v82, 0x3dd53b94, v151
	v_fmamk_f32 v213, v83, 0x3dd53b94, v151
	v_fmamk_f32 v214, v84, 0x3dd53b94, v151
	v_fmamk_f32 v215, v85, 0x3dd53b94, v151
	v_fmamk_f32 v216, v86, 0x3dd53b94, v151
	v_fmamk_f32 v217, v87, 0x3dd53b94, v151
	v_fmamk_f32 v218, v88, 0x3dd53b94, v151
	v_fmamk_f32 v219, v89, 0x3dd53b94, v151
	v_fmamk_f32 v220, v90, 0x3dd53b94, v151
	v_fmamk_f32 v221, v91, 0x3dd53b94, v151
	v_fmamk_f32 v225, v92, 0x3dd53b94, v151
	v_fmamk_f32 v226, v93, 0x3dd53b94, v151
	v_fmamk_f32 v227, v94, 0x3dd53b94, v151
	v_fmac_f32_e32 v151, 0x3dd53b94, v95
	v_exp_f32_e32 v208, v64
	v_exp_f32_e32 v210, v65
	v_exp_f32_e32 v206, v66
	v_exp_f32_e32 v209, v67
	v_exp_f32_e32 v163, v68
	v_exp_f32_e32 v207, v69
	v_exp_f32_e32 v162, v70
	v_exp_f32_e32 v205, v71
	v_exp_f32_e32 v159, v72
	v_exp_f32_e32 v161, v73
	v_exp_f32_e32 v157, v74
	v_exp_f32_e32 v160, v75
	v_exp_f32_e32 v155, v76
	v_exp_f32_e32 v158, v77
	v_exp_f32_e32 v154, v78
	v_exp_f32_e32 v156, v79
	s_waitcnt lgkmcnt(0)
	s_barrier
	s_setprio 1
	ds_read_b128 v[64:67], v199 offset:32768
	ds_read_b128 v[96:99], v199 offset:32800
	s_waitcnt lgkmcnt(1)
	v_mfma_f32_32x32x16_bf16 v[80:95], v[64:67], v[140:143], 0
	ds_read_b128 v[64:67], v199 offset:45568
	ds_read_b128 v[100:103], v199 offset:45600
	ds_read_b128 v[104:107], v199 offset:32832
	ds_read_b128 v[108:111], v199 offset:32864
	ds_read_b128 v[246:249], v199 offset:45632
	ds_read_b128 v[250:253], v199 offset:45664
	s_waitcnt lgkmcnt(5)
	v_mfma_f32_32x32x16_bf16 v[64:79], v[64:67], v[140:143], 0
	v_mfma_f32_32x32x16_bf16 v[80:95], v[96:99], v[136:139], v[80:95]
	ds_read_b128 v[96:99], v199 offset:32896
	s_waitcnt lgkmcnt(5)
	v_mfma_f32_32x32x16_bf16 v[64:79], v[100:103], v[136:139], v[64:79]
	ds_read_b128 v[100:103], v199 offset:32928
	s_waitcnt lgkmcnt(5)
	v_mfma_f32_32x32x16_bf16 v[80:95], v[104:107], v[132:135], v[80:95]
	ds_read_b128 v[104:107], v199 offset:45696
	s_waitcnt lgkmcnt(4)
	v_mfma_f32_32x32x16_bf16 v[64:79], v[246:249], v[132:135], v[64:79]
	v_mfma_f32_32x32x16_bf16 v[80:95], v[108:111], v[128:131], v[80:95]
	ds_read_b128 v[108:111], v199 offset:45728
	ds_read_b128 v[246:249], v199 offset:32960
	s_waitcnt lgkmcnt(5)
	v_mfma_f32_32x32x16_bf16 v[64:79], v[250:253], v[128:131], v[64:79]
	ds_read_b128 v[250:253], v199 offset:32992
	s_waitcnt lgkmcnt(5)
	v_mfma_f32_32x32x16_bf16 v[80:95], v[96:99], v[124:127], v[80:95]
	ds_read_b128 v[96:99], v199 offset:45760
	s_waitcnt lgkmcnt(4)
	v_mfma_f32_32x32x16_bf16 v[64:79], v[104:107], v[124:127], v[64:79]
	v_mfma_f32_32x32x16_bf16 v[80:95], v[100:103], v[120:123], v[80:95]
	ds_read_b128 v[100:103], v199 offset:45792
	ds_read_b128 v[104:107], v199 offset:33024
	s_waitcnt lgkmcnt(5)
	v_mfma_f32_32x32x16_bf16 v[64:79], v[108:111], v[120:123], v[64:79]
	ds_read_b128 v[108:111], v193
	s_waitcnt lgkmcnt(5)
; __device__ __forceinline__ void partialSM(f32x16& p0, f32x16& p1, float& m_reg, float& mn, float& alpha) {
;   constexpr float C = SCALE * 1.4426950408889634f;
;   float pmax = p0[0];
; #pragma unroll
;   for (int r = 1; r < 16; ++r) pmax = fmaxf(pmax, p0[r]);
; #pragma unroll
;   for (int r = 0; r < 16; ++r) pmax = fmaxf(pmax, p1[r]);
;   { auto rr = __builtin_amdgcn_permlane32_swap(__float_as_uint(pmax), __float_as_uint(pmax), false, false);
;     pmax = fmaxf(__uint_as_float(rr[0]), __uint_as_float(rr[1])); }
;   if (__builtin_expect(__all(pmax - m_reg <= THR / SCALE), 1)) { mn = m_reg; alpha = 1.f; }
;   else { mn = fmaxf(m_reg, pmax); alpha = __builtin_amdgcn_exp2f((m_reg - mn) * C); m_reg = mn; }
;   float mnC = -mn * C;
; #pragma unroll
;   for (int r = 0; r < 16; ++r) p0[r] = fmaf(p0[r], C, mnC);
; #pragma unroll
;   for (int r = 0; r < 16; ++r) p1[r] = fmaf(p1[r], C, mnC);
; #pragma unroll
;   for (int r = 0; r < 16; ++r) p0[r] = __builtin_amdgcn_exp2f(p0[r]);
; }
; __device__ __forceinline__ void finishSM(f32x16& p0, f32x16& p1, float alpha, float& l_reg, bf16x8& pa0, bf16x8& pa1, bf16x8& pa2, bf16x8& pa3) {
; #pragma unroll
;   for (int r = 0; r < 16; ++r) p1[r] = __builtin_amdgcn_exp2f(p1[r]);
;   float ps = 0;
; #pragma unroll
;   for (int r = 0; r < 16; ++r) ps += p0[r];
; #pragma unroll
;   for (int r = 0; r < 16; ++r) ps += p1[r];
;   { auto rr = __builtin_amdgcn_permlane32_swap(__float_as_uint(ps), __float_as_uint(ps), false, false);
;     ps = __uint_as_float(rr[0]) + __uint_as_float(rr[1]); }
;   l_reg = l_reg * alpha + ps;
;     ...
;   MLA_PK4(p0, 0, pa0); MLA_PK4(p0, 8, pa1); MLA_PK4(p1, 0, pa2); MLA_PK4(p1, 8, pa3);
;     ...
; }
; __device__ __forceinline__ void qkt(f32x16& p0, f32x16& p1, const unsigned Ks, const bf16x8* qr, const unsigned qrl, int r32, int hi) {
;   p0 = f32x16{}; p1 = f32x16{}; __builtin_amdgcn_s_setprio(1);
; #pragma unroll
;   for (int dg = 0; dg < 3; ++dg) {
; #pragma unroll
;     for (int d4 = 0; d4 < 4; ++d4) { const int d0 = dg * 4 + d4;
;       const bf16x8 b0 = *(const LAS bf16x8*)(size_t)(Ks + (unsigned)(r32 * KROW + hi * 16) + (unsigned)(d0 * 32));
;       const bf16x8 b1 = *(const LAS bf16x8*)(size_t)(Ks + (unsigned)(r32 * KROW + hi * 16) + (unsigned)(32 * KROW + d0 * 32));
;       const bf16x8 qv = (dg < 2) ? qr[d0 & 7] : *(const LAS bf16x8*)(size_t)(qrl + (unsigned)(d4 * 32));
	v_mfma_f32_32x32x16_bf16 v[80:95], v[246:249], v[116:119], v[80:95]
	ds_read_b128 v[246:249], v199 offset:33056
	s_waitcnt lgkmcnt(4)
	v_mfma_f32_32x32x16_bf16 v[64:79], v[96:99], v[116:119], v[64:79]
	v_mfma_f32_32x32x16_bf16 v[80:95], v[250:253], v[112:115], v[80:95]
	ds_read_b128 v[250:253], v199 offset:45824
	ds_read_b128 v[96:99], v199 offset:45856
	s_waitcnt lgkmcnt(5)
	v_mfma_f32_32x32x16_bf16 v[64:79], v[100:103], v[112:115], v[64:79]
	ds_read_b128 v[100:103], v195
	s_waitcnt lgkmcnt(4)
	v_mfma_f32_32x32x16_bf16 v[80:95], v[104:107], v[108:111], v[80:95]
	ds_read_b128 v[104:107], v199 offset:33088
	s_waitcnt lgkmcnt(3)
	v_mfma_f32_32x32x16_bf16 v[64:79], v[250:253], v[108:111], v[64:79]
	ds_read_b128 v[108:111], v196
	s_waitcnt lgkmcnt(2)
	v_mfma_f32_32x32x16_bf16 v[80:95], v[246:249], v[100:103], v[80:95]
	ds_read_b128 v[246:249], v199 offset:33120
	ds_read_b128 v[250:253], v199 offset:45888
	v_mfma_f32_32x32x16_bf16 v[64:79], v[96:99], v[100:103], v[64:79]
	ds_read_b128 v[96:99], v199 offset:45920
	ds_read_b128 v[100:103], v194
	s_waitcnt lgkmcnt(4)
	v_mfma_f32_32x32x16_bf16 v[80:95], v[104:107], v[108:111], v[80:95]
	s_waitcnt lgkmcnt(2)
	v_mfma_f32_32x32x16_bf16 v[64:79], v[250:253], v[108:111], v[64:79]
	s_waitcnt lgkmcnt(0)
	v_mfma_f32_32x32x16_bf16 v[80:95], v[246:249], v[100:103], v[80:95]
	v_mfma_f32_32x32x16_bf16 v[64:79], v[96:99], v[100:103], v[64:79]
	s_setprio 0
	v_add_co_u32_e32 v96, vcc, s80, v180
	s_nop 1
	v_addc_co_u32_e32 v97, vcc, 0, v181, vcc
	v_add_co_u32_e32 v100, vcc, s80, v182
	s_nop 1
	v_addc_co_u32_e32 v101, vcc, 0, v183, vcc
	v_add_co_u32_e32 v104, vcc, s80, v184
	global_load_dwordx4 v[96:99], v[96:97], off
	s_nop 0
	global_load_dwordx4 v[100:103], v[100:101], off
	v_addc_co_u32_e32 v105, vcc, 0, v185, vcc
	v_add_co_u32_e32 v108, vcc, s80, v186
	s_nop 1
	v_addc_co_u32_e32 v109, vcc, 0, v187, vcc
	v_add_co_u32_e32 v144, vcc, s76, v178
	global_load_dwordx4 v[104:107], v[104:105], off
	s_nop 0
	global_load_dwordx4 v[108:111], v[108:109], off
	v_addc_co_u32_e32 v145, vcc, 0, v179, vcc
	global_load_dwordx4 v[144:147], v[144:145], off
	v_max_f32_e32 v153, v81, v81
	v_max_f32_e32 v180, v80, v80
	v_max_f32_e32 v153, v180, v153
	v_max3_f32 v153, v153, v82, v83
	v_max3_f32 v153, v153, v84, v85
	v_max3_f32 v153, v153, v86, v87
	v_max3_f32 v153, v153, v88, v89
	v_max3_f32 v153, v153, v90, v91
	v_max3_f32 v153, v153, v92, v93
	v_max3_f32 v153, v153, v94, v95
	v_max3_f32 v153, v153, v64, v65
	v_max3_f32 v153, v153, v66, v67
	v_max3_f32 v153, v153, v68, v69
	v_max3_f32 v153, v153, v70, v71
	v_max3_f32 v153, v153, v72, v73
	v_max3_f32 v153, v153, v74, v75
	v_max3_f32 v153, v153, v76, v77
	v_max3_f32 v153, v153, v78, v79
	v_mov_b32_e32 v180, v153
	s_nop 1
	v_permlane32_swap_b32_e32 v153, v180
	v_max_f32_e32 v180, v180, v180
	v_max_f32_e32 v153, v153, v153
	v_max_f32_e32 v153, v153, v180
	v_max_f32_e32 v181, v150, v150
	v_sub_f32_e32 v180, v153, v150
	v_max_f32_e32 v153, v181, v153
	v_sub_f32_e32 v181, v150, v153
	v_mul_f32_e32 v181, 0x3dd53b94, v181
	v_exp_f32_e32 v181, v181
	v_cmp_ge_f32_e32 vcc, s75, v180
	s_cmp_eq_u64 vcc, exec
	s_cselect_b64 s[4:5], -1, 0
	v_cndmask_b32_e64 v182, v181, 1.0, s[4:5]
	v_exp_f32_e32 v181, v211
	v_exp_f32_e32 v211, v213
	v_exp_f32_e32 v213, v215
	v_exp_f32_e32 v215, v217
	v_exp_f32_e32 v217, v219
	v_exp_f32_e32 v219, v221
	v_exp_f32_e32 v221, v226
	v_exp_f32_e32 v226, v151
	v_add_f32_e32 v151, 0, v208
	v_add_f32_e32 v151, v210, v151
	v_add_f32_e32 v151, v206, v151
	v_add_f32_e32 v151, v209, v151
	v_add_f32_e32 v151, v163, v151
	v_add_f32_e32 v151, v207, v151
	v_add_f32_e32 v151, v162, v151
	v_add_f32_e32 v151, v205, v151
	v_add_f32_e32 v151, v159, v151
	v_add_f32_e32 v151, v161, v151
	v_add_f32_e32 v151, v157, v151
	v_add_f32_e32 v151, v160, v151
	v_exp_f32_e32 v180, v152
	v_add_f32_e32 v151, v155, v151
	v_add_f32_e32 v151, v158, v151
	v_exp_f32_e32 v183, v212
	v_add_f32_e32 v151, v154, v151
	v_add_f32_e32 v151, v156, v151
	v_exp_f32_e32 v212, v214
	v_add_f32_e32 v151, v180, v151
	v_add_f32_e32 v151, v181, v151
	v_exp_f32_e32 v214, v216
	v_add_f32_e32 v151, v183, v151
	v_add_f32_e32 v151, v211, v151
	v_exp_f32_e32 v216, v218
	v_add_f32_e32 v151, v212, v151
	v_add_f32_e32 v151, v213, v151
	v_exp_f32_e32 v218, v220
	v_add_f32_e32 v151, v214, v151
	v_add_f32_e32 v151, v215, v151
	v_exp_f32_e32 v220, v225
	v_add_f32_e32 v151, v216, v151
	v_add_f32_e32 v151, v217, v151
	v_exp_f32_e32 v225, v227
	v_add_f32_e32 v151, v218, v151
	v_add_f32_e32 v151, v219, v151
	v_add_f32_e32 v151, v220, v151
	v_add_f32_e32 v151, v221, v151
	v_add_f32_e32 v151, v225, v151
	v_add_f32_e32 v151, v226, v151
	v_mov_b32_e32 v152, v151
	s_nop 1
	v_permlane32_swap_b32_e32 v151, v152
	v_cvt_pk_bf16_f32 v184, v208, v210
	v_cvt_pk_bf16_f32 v185, v206, v209
	v_cvt_pk_bf16_f32 v186, v163, v207
	v_cvt_pk_bf16_f32 v187, v162, v205
	v_cvt_pk_bf16_f32 v206, v159, v161
	v_cvt_pk_bf16_f32 v207, v157, v160
	v_cvt_pk_bf16_f32 v208, v155, v158
	v_cvt_pk_bf16_f32 v209, v154, v156
	v_cvt_pk_bf16_f32 v154, v180, v181
	v_cvt_pk_bf16_f32 v155, v183, v211
	v_cvt_pk_bf16_f32 v156, v212, v213
	v_cvt_pk_bf16_f32 v157, v214, v215
	v_cvt_pk_bf16_f32 v158, v216, v217
	v_cvt_pk_bf16_f32 v159, v218, v219
	v_cvt_pk_bf16_f32 v160, v220, v221
	v_cvt_pk_bf16_f32 v161, v225, v226
	s_nop 0
	v_permlane32_swap_b32_e32 v184, v186
	v_permlane32_swap_b32_e32 v185, v187
	v_permlane32_swap_b32_e32 v206, v208
	v_permlane32_swap_b32_e32 v207, v209
	v_permlane32_swap_b32_e32 v154, v156
	v_permlane32_swap_b32_e32 v155, v157
	v_permlane32_swap_b32_e32 v158, v160
	v_permlane32_swap_b32_e32 v159, v161
	s_setprio 1
	ds_read_b64_tr_b16 v[210:211], v197 offset:0
	ds_read_b64_tr_b16 v[212:213], v197 offset:0x800
	ds_read_b64_tr_b16 v[214:215], v197 offset:0x1000
	ds_read_b64_tr_b16 v[216:217], v197 offset:0x1800
	ds_read_b64_tr_b16 v[218:219], v197 offset:0x2000
	ds_read_b64_tr_b16 v[220:221], v197 offset:0x2800
	ds_read_b64_tr_b16 v[226:227], v197 offset:0x3000
	ds_read_b64_tr_b16 v[228:229], v197 offset:0x3800
	s_waitcnt lgkmcnt(0)
; #define MLA_SBAR() __builtin_amdgcn_sched_barrier(0)
; #define MLA_SWAIT() asm volatile("s_waitcnt vmcnt(0)" ::: "memory")
; #define MLA_RESC(a) do { if (__any((a) < 1.f)) { if (hi == 0) al_l[r32] = (a); asm volatile("s_waitcnt lgkmcnt(0)" ::: "memory"); \
;     _Pragma("unroll") for (int d = 0; d < 4; ++d) _Pragma("unroll") for (int r = 0; r < 16; ++r) o[d][r] *= al_l[crow(r, hi)]; } } while (0)
; template <int D0> __device__ __forceinline__ void pv_one(f32x16& od, int vb, bf16x8 pa0, bf16x8 pa1, bf16x8 pa2, bf16x8 pa3) {
;   const s16x4 l0 = tr_read<v_rd_off(D0, 0, 0)>(vb), h0 = tr_read<v_rd_off(D0, 0, 1)>(vb), l1 = tr_read<v_rd_off(D0, 1, 0)>(vb), h1 = tr_read<v_rd_off(D0, 1, 1)>(vb);
;   const s16x4 l2 = tr_read<v_rd_off(D0, 2, 0)>(vb), h2 = tr_read<v_rd_off(D0, 2, 1)>(vb), l3 = tr_read<v_rd_off(D0, 3, 0)>(vb), h3 = tr_read<v_rd_off(D0, 3, 1)>(vb);
;   asm volatile("s_waitcnt lgkmcnt(0)" ::: "memory"); MLA_SBAR();
;     ...
;   od = __builtin_amdgcn_mfma_f32_32x32x16_bf16(pa0, MLA_PK(l0, h0), od, 0, 0, 0);
;   od = __builtin_amdgcn_mfma_f32_32x32x16_bf16(pa1, MLA_PK(l1, h1), od, 0, 0, 0);
;   od = __builtin_amdgcn_mfma_f32_32x32x16_bf16(pa2, MLA_PK(l2, h2), od, 0, 0, 0);
;   od = __builtin_amdgcn_mfma_f32_32x32x16_bf16(pa3, MLA_PK(l3, h3), od, 0, 0, 0);
;     ...
; }
; __device__ __forceinline__ void pv_d0(f32x16* o, int vb, bf16x8 pa0, bf16x8 pa1, bf16x8 pa2, bf16x8 pa3) {
;   __builtin_amdgcn_s_setprio(1);
;   pv_one<0>(o[0], vb, pa0, pa1, pa2, pa3); pv_one<1>(o[1], vb, pa0, pa1, pa2, pa3); pv_one<2>(o[2], vb, pa0, pa1, pa2, pa3); pv_one<3>(o[3], vb, pa0, pa1, pa2, pa3);
;   __builtin_amdgcn_s_setprio(0);
; }
; __device__ __forceinline__ void attn_body(const GAS bf16* __restrict__ Qb, const int ldq, const GAS bf16* __restrict__ Kn, const GAS bf16* __restrict__ Vh, const int ldkv, const GAS bf16* __restrict__ Kr, ...
;     ...
;     __syncthreads(); MLA_SWAIT(); MLA_SWRITE(1);
;     MLA_RESC(alA); __syncthreads();
	s_nop 0
	v_mfma_f32_32x32x16_bf16 v[0:15], v[184:187], v[210:213], v[0:15]
	ds_read_b64_tr_b16 v[210:211], v197 offset:0x200
	ds_read_b64_tr_b16 v[212:213], v197 offset:0xa00
	v_mfma_f32_32x32x16_bf16 v[0:15], v[206:209], v[214:217], v[0:15]
	ds_read_b64_tr_b16 v[214:215], v197 offset:0x1200
	ds_read_b64_tr_b16 v[216:217], v197 offset:0x1a00
	v_mfma_f32_32x32x16_bf16 v[0:15], v[154:157], v[218:221], v[0:15]
	ds_read_b64_tr_b16 v[218:219], v197 offset:0x2200
	ds_read_b64_tr_b16 v[220:221], v197 offset:0x2a00
	v_mfma_f32_32x32x16_bf16 v[0:15], v[158:161], v[226:229], v[0:15]
	ds_read_b64_tr_b16 v[226:227], v197 offset:0x3200
	ds_read_b64_tr_b16 v[228:229], v197 offset:0x3a00
	s_waitcnt lgkmcnt(0)
	v_mfma_f32_32x32x16_bf16 v[48:63], v[184:187], v[210:213], v[48:63]
	ds_read_b64_tr_b16 v[210:211], v197 offset:0x400
	ds_read_b64_tr_b16 v[212:213], v197 offset:0xc00
	v_mfma_f32_32x32x16_bf16 v[48:63], v[206:209], v[214:217], v[48:63]
	ds_read_b64_tr_b16 v[214:215], v197 offset:0x1400
	ds_read_b64_tr_b16 v[216:217], v197 offset:0x1c00
	v_mfma_f32_32x32x16_bf16 v[48:63], v[154:157], v[218:221], v[48:63]
	ds_read_b64_tr_b16 v[218:219], v197 offset:0x2400
	ds_read_b64_tr_b16 v[220:221], v197 offset:0x2c00
	v_mfma_f32_32x32x16_bf16 v[48:63], v[158:161], v[226:229], v[48:63]
	ds_read_b64_tr_b16 v[226:227], v197 offset:0x3400
	ds_read_b64_tr_b16 v[228:229], v197 offset:0x3c00
	s_waitcnt lgkmcnt(0)
	v_mfma_f32_32x32x16_bf16 v[32:47], v[184:187], v[210:213], v[32:47]
	ds_read_b64_tr_b16 v[210:211], v197 offset:0x600
	ds_read_b64_tr_b16 v[212:213], v197 offset:0xe00
	v_mfma_f32_32x32x16_bf16 v[32:47], v[206:209], v[214:217], v[32:47]
	ds_read_b64_tr_b16 v[214:215], v197 offset:0x1600
	ds_read_b64_tr_b16 v[216:217], v197 offset:0x1e00
	v_mfma_f32_32x32x16_bf16 v[32:47], v[154:157], v[218:221], v[32:47]
	ds_read_b64_tr_b16 v[218:219], v197 offset:0x2600
	ds_read_b64_tr_b16 v[220:221], v197 offset:0x2e00
	v_mfma_f32_32x32x16_bf16 v[32:47], v[158:161], v[226:229], v[32:47]
	ds_read_b64_tr_b16 v[226:227], v197 offset:0x3600
	ds_read_b64_tr_b16 v[228:229], v197 offset:0x3e00
	s_waitcnt lgkmcnt(0)
	v_mfma_f32_32x32x16_bf16 v[16:31], v[184:187], v[210:213], v[16:31]
	v_mfma_f32_32x32x16_bf16 v[16:31], v[206:209], v[214:217], v[16:31]
	v_mfma_f32_32x32x16_bf16 v[16:31], v[154:157], v[218:221], v[16:31]
	v_mfma_f32_32x32x16_bf16 v[16:31], v[158:161], v[226:229], v[16:31]
	s_setprio 0
	s_barrier
	s_waitcnt vmcnt(0)
	v_cmp_gt_f32_e32 vcc, 1.0, v182
	s_waitcnt vmcnt(4)
	ds_write_b128 v200, v[96:99] offset:16384
	s_waitcnt vmcnt(3)
	ds_write_b128 v201, v[100:103] offset:16384
	s_waitcnt vmcnt(2)
	ds_write_b128 v148, v[104:107] offset:58368
	s_waitcnt vmcnt(1)
	ds_write_b128 v204, v[108:111] offset:12800
	s_waitcnt vmcnt(0)
	ds_write_b128 v149, v[144:147] offset:58368
	s_cbranch_vccz .LBB0_2654
	s_and_saveexec_b64 s[62:63], s[2:3]
	ds_write_b32 v177, v182 offset:128
	s_or_b64 exec, exec, s[62:63]
	s_waitcnt lgkmcnt(0)
	v_add_u32_e32 v110, v167, v164
	ds_read2_b32 v[96:97], v110 offset0:48 offset1:49
	ds_read2_b32 v[98:99], v110 offset0:50 offset1:51
	ds_read2_b32 v[100:101], v110 offset0:56 offset1:57
	ds_read2_b32 v[102:103], v110 offset0:58 offset1:59
	ds_read2_b32 v[104:105], v110 offset0:32 offset1:33
	ds_read2_b32 v[106:107], v110 offset0:34 offset1:35
	ds_read2_b32 v[108:109], v110 offset0:40 offset1:41
	ds_read2_b32 v[110:111], v110 offset0:42 offset1:43
	s_waitcnt lgkmcnt(4)
	v_pk_mul_f32 v[14:15], v[14:15], v[102:103]
	v_pk_mul_f32 v[12:13], v[12:13], v[100:101]
	v_pk_mul_f32 v[10:11], v[10:11], v[98:99]
	v_pk_mul_f32 v[8:9], v[8:9], v[96:97]
	s_waitcnt lgkmcnt(0)
	v_pk_mul_f32 v[6:7], v[6:7], v[110:111]
	v_pk_mul_f32 v[4:5], v[4:5], v[108:109]
	v_pk_mul_f32 v[2:3], v[2:3], v[106:107]
	v_pk_mul_f32 v[0:1], v[0:1], v[104:105]
	v_pk_mul_f32 v[62:63], v[62:63], v[102:103]
	v_pk_mul_f32 v[60:61], v[60:61], v[100:101]
	v_pk_mul_f32 v[58:59], v[58:59], v[98:99]
	v_pk_mul_f32 v[56:57], v[56:57], v[96:97]
	v_pk_mul_f32 v[54:55], v[54:55], v[110:111]
	v_pk_mul_f32 v[52:53], v[52:53], v[108:109]
	v_pk_mul_f32 v[50:51], v[50:51], v[106:107]
	v_pk_mul_f32 v[48:49], v[48:49], v[104:105]
	v_pk_mul_f32 v[46:47], v[46:47], v[102:103]
	v_pk_mul_f32 v[44:45], v[44:45], v[100:101]
	v_pk_mul_f32 v[42:43], v[42:43], v[98:99]
	v_pk_mul_f32 v[40:41], v[40:41], v[96:97]
	v_pk_mul_f32 v[38:39], v[38:39], v[110:111]
	v_pk_mul_f32 v[36:37], v[36:37], v[108:109]
	v_pk_mul_f32 v[34:35], v[34:35], v[106:107]
	v_pk_mul_f32 v[32:33], v[32:33], v[104:105]
	v_pk_mul_f32 v[30:31], v[30:31], v[102:103]
	v_pk_mul_f32 v[28:29], v[28:29], v[100:101]
	v_pk_mul_f32 v[26:27], v[26:27], v[98:99]
	v_pk_mul_f32 v[24:25], v[24:25], v[96:97]
	v_pk_mul_f32 v[22:23], v[22:23], v[110:111]
	v_pk_mul_f32 v[20:21], v[20:21], v[108:109]
	v_pk_mul_f32 v[18:19], v[18:19], v[106:107]
	v_pk_mul_f32 v[16:17], v[16:17], v[104:105]
